# GEMM phases P1/P4/P6/P7/P9b: first K-iteration of each tile peeled, its first MFMA per accumulator takes C=0; the 128 per-tile zeroing v_mov deleted
# speedup vs baseline: 1.0068x; 1.0068x over previous
;     __device__ bool next(int i, Unit& u) const { if (!b.next(i >> 1, u)) return false; u.half = i & 1; u.koff = (i & 1) * kbytes; return true; }
; #define PG8_STAGE(bufoff, gbase, voff) do { _Pragma("unroll") for (int _i = 0; _i < 2; ++_i) \
;         __builtin_amdgcn_global_load_lds((const unsigned*)((const char*)(gbase) + (voff)[_i]), (LAS unsigned*)(lds + (bufoff) + ldsw + _i * 8192), 16, 0, 0); } while (0)
; #define PG8_LDA(dst, b, h) do { _Pragma("unroll") for (int m = 0; m < 4; ++m) _Pragma("unroll") for (int k = 0; k < 2; ++k) dst[m][k] = *(const LAS bf16x8*)(lds + PG8_SA(b, h) + aoff + m * 2048 + k * 1024); } while (0)
; #define PG8_LDB(dst, b, h) do { _Pragma("unroll") for (int n = 0; n < 2; ++n) _Pragma("unroll") for (int k = 0; k < 2; ++k) dst[n][k] = *(const LAS bf16x8*)(lds + PG8_SB(b, h) + boff + n * 2048 + k * 1024); } while (0)
; #define PG8_WAIT_V(n) asm volatile("s_waitcnt vmcnt(" #n ")" ::: "memory")
; #define PG8_WAIT_L(n) asm volatile("s_waitcnt lgkmcnt(" #n ")" ::: "memory")
; #define PG8_BAR __builtin_amdgcn_s_barrier()
; #define PG8_SCHED __builtin_amdgcn_sched_barrier(0)
; template <class Epi, class Sched>
; __device__ __forceinline__ void gemm_phase(LAS unsigned char* lds, const Gemm g, const Sched& S, const Epi& E, int tid_in) {
;     ...
;         const bool has_next = S.next(ui + 1, nxt);
;         const char* nA = has_next ? (const char*)g.A + (size_t)nxt.pm * tstep + nxt.koff : cA; const char* nB = has_next ? (const char*)g.Bt + (size_t)nxt.pn * tstep + nxt.koff : cB;
;         for (int t = 0; t < nt; t += 2) {
;             const bool last = (t == nt - 2);
;             const char* a1 = cA + (size_t)(t + 1) * kstep;
;             const char* a2 = last ? nA : cA + (size_t)(t + 2) * kstep; const char* b2 = last ? nB : cB + (size_t)(t + 2) * kstep;
;             const char* a3 = a2 + kstep; const char* b3 = b2 + kstep;
;             PG8_LDB(B0, 0, 0); PG8_LDB(B1, 0, 1); PG8_SCHED; PG8_LDA(At, 0, 0); PG8_STAGE(PG8_SA(1, 0), a1, voffA); PG8_STAGE(PG8_SA(1, 1), a1 + hstep, voffA);
;             PG8_WAIT_V(8); PG8_WAIT_L(0); PG8_BAR; PG8_MMA(0, 0, At, B0); PG8_MMA(0, 1, At, B1); PG8_BAR; PG8_SCHED;
;             PG8_LDA(At, 0, 1); PG8_STAGE(PG8_SB(0, 0), b2, voffB); PG8_STAGE(PG8_SB(0, 1), b2 + hstep, voffB);
;             PG8_WAIT_V(6); PG8_WAIT_L(0); PG8_BAR; PG8_MMA(1, 0, At, B0); PG8_MMA(1, 1, At, B1); PG8_BAR; PG8_SCHED;
.LBB0_101:
	s_ashr_i32 s31, s30, 31
	s_lshl_b64 s[34:35], s[30:31], 20
	s_add_u32 s34, s58, s34
	s_addc_u32 s35, s59, s35
	s_and_b64 s[36:37], s[0:1], exec
	s_cselect_b32 s31, s35, s43
	s_cselect_b32 s39, s34, s42
	s_ashr_i32 s29, s28, 31
	s_lshl_b64 s[36:37], s[28:29], 20
	s_add_u32 s36, s56, s36
	s_addc_u32 s37, s57, s37
	s_and_b64 s[46:47], s[0:1], exec
	s_cselect_b32 s29, s37, s45
	s_cselect_b32 s41, s36, s44
	s_add_u32 s94, s44, 0x100
	s_addc_u32 s95, s45, 0
	s_mov_b32 s96, -2
	s_mov_b64 s[44:45], 0
	v_lshl_add_u64 v[128:129], s[42:43], 0, v[158:159]
	v_lshl_add_u64 v[130:131], s[42:43], 0, v[160:161]
	ds_read_b128 v[132:135], v179
	ds_read_b128 v[136:139], v179 offset:1024
	ds_read_b128 v[140:143], v179 offset:2048
	ds_read_b128 v[172:175], v179 offset:3072
	ds_read_b128 v[188:191], v180
	ds_read_b128 v[192:195], v180 offset:1024
	ds_read_b128 v[196:199], v180 offset:2048
	ds_read_b128 v[200:203], v180 offset:3072
	s_add_u32 s46, s42, s44
	s_addc_u32 s47, s43, s45
	s_add_u32 s48, s46, 0x100
	s_addc_u32 s49, s47, 0
	s_add_u32 s46, s94, s44
	s_addc_u32 s47, s95, s45
	s_cmpk_eq_i32 s44, 0xf00
	s_cselect_b32 s47, s29, s47
	s_cselect_b32 s46, s41, s46
	s_cselect_b32 s49, s31, s49
	s_cselect_b32 s48, s39, s48
	v_lshl_add_u64 v[168:169], v[130:131], 0, s[44:45]
	v_lshl_add_u64 v[176:177], v[168:169], 0, s[10:11]
	s_add_i32 m0, s60, 0x8000
	ds_read_b128 v[204:207], v181
	ds_read_b128 v[208:211], v181 offset:1024
	ds_read_b128 v[212:215], v181 offset:2048
	ds_read_b128 v[216:219], v181 offset:3072
	ds_read_b128 v[220:223], v181 offset:4096
	ds_read_b128 v[224:227], v181 offset:5120
	ds_read_b128 v[228:231], v181 offset:6144
	ds_read_b128 v[232:235], v181 offset:7168
	global_load_lds_dwordx4 v[176:177], off
	v_lshl_add_u64 v[176:177], v[128:129], 0, s[44:45]
	v_lshl_add_u64 v[184:185], v[176:177], 0, s[10:11]
	s_add_i32 m0, s60, 0xa000
	v_lshl_add_u64 v[168:169], v[168:169], 0, s[12:13]
	global_load_lds_dwordx4 v[184:185], off
	s_add_i32 m0, s60, 0xc000
	s_nop 0
	global_load_lds_dwordx4 v[168:169], off
	v_lshl_add_u64 v[168:169], v[176:177], 0, s[12:13]
	s_add_i32 m0, s60, 0xe000
	s_nop 0
	global_load_lds_dwordx4 v[168:169], off
	s_waitcnt vmcnt(8)
	s_waitcnt lgkmcnt(0)
	s_barrier
	s_setprio 3
	s_waitcnt lgkmcnt(0)
	v_mfma_f32_16x16x32_bf16 v[124:127], v[132:135], v[204:207], 0
	v_mfma_f32_16x16x32_bf16 v[120:123], v[140:143], v[204:207], 0
	v_mfma_f32_16x16x32_bf16 v[108:111], v[132:135], v[212:215], 0
	v_mfma_f32_16x16x32_bf16 v[104:107], v[140:143], v[212:215], 0
	v_mfma_f32_16x16x32_bf16 v[92:95], v[132:135], v[220:223], 0
	v_mfma_f32_16x16x32_bf16 v[88:91], v[140:143], v[220:223], 0
	v_mfma_f32_16x16x32_bf16 v[76:79], v[132:135], v[228:231], 0
	v_mfma_f32_16x16x32_bf16 v[72:75], v[140:143], v[228:231], 0
	v_mfma_f32_16x16x32_bf16 v[124:127], v[136:139], v[208:211], v[124:127]
	v_mfma_f32_16x16x32_bf16 v[120:123], v[172:175], v[208:211], v[120:123]
	v_mfma_f32_16x16x32_bf16 v[108:111], v[136:139], v[216:219], v[108:111]
	v_mfma_f32_16x16x32_bf16 v[104:107], v[172:175], v[216:219], v[104:107]
	v_mfma_f32_16x16x32_bf16 v[92:95], v[136:139], v[224:227], v[92:95]
	v_mfma_f32_16x16x32_bf16 v[88:91], v[172:175], v[224:227], v[88:91]
	v_mfma_f32_16x16x32_bf16 v[76:79], v[136:139], v[232:235], v[76:79]
	v_mfma_f32_16x16x32_bf16 v[72:75], v[172:175], v[232:235], v[72:75]
	s_setprio 0
	s_setprio 3
	v_mfma_f32_16x16x32_bf16 v[116:119], v[188:191], v[204:207], 0
	v_mfma_f32_16x16x32_bf16 v[112:115], v[196:199], v[204:207], 0
	v_mfma_f32_16x16x32_bf16 v[100:103], v[188:191], v[212:215], 0
	v_mfma_f32_16x16x32_bf16 v[96:99], v[196:199], v[212:215], 0
	v_mfma_f32_16x16x32_bf16 v[84:87], v[188:191], v[220:223], 0
	v_mfma_f32_16x16x32_bf16 v[80:83], v[196:199], v[220:223], 0
	v_mfma_f32_16x16x32_bf16 v[68:71], v[188:191], v[228:231], 0
	v_mfma_f32_16x16x32_bf16 v[64:67], v[196:199], v[228:231], 0
	v_mfma_f32_16x16x32_bf16 v[116:119], v[192:195], v[208:211], v[116:119]
	v_mfma_f32_16x16x32_bf16 v[112:115], v[200:203], v[208:211], v[112:115]
	v_mfma_f32_16x16x32_bf16 v[100:103], v[192:195], v[216:219], v[100:103]
	v_mfma_f32_16x16x32_bf16 v[96:99], v[200:203], v[216:219], v[96:99]
	v_mfma_f32_16x16x32_bf16 v[84:87], v[192:195], v[224:227], v[84:87]
	v_mfma_f32_16x16x32_bf16 v[80:83], v[200:203], v[224:227], v[80:83]
	v_mfma_f32_16x16x32_bf16 v[68:71], v[192:195], v[232:235], v[68:71]
	v_mfma_f32_16x16x32_bf16 v[64:67], v[200:203], v[232:235], v[64:67]
	s_setprio 0
	s_barrier
	s_add_i32 s97, s66, s2
	v_lshl_add_u64 v[168:169], s[46:47], 0, v[148:149]
	s_mov_b32 m0, s97
	ds_read_b128 v[204:207], v181 offset:16384
	ds_read_b128 v[208:211], v181 offset:17408
	ds_read_b128 v[212:215], v181 offset:18432
	ds_read_b128 v[216:219], v181 offset:19456
	ds_read_b128 v[220:223], v181 offset:20480
	ds_read_b128 v[224:227], v181 offset:21504
	ds_read_b128 v[228:231], v181 offset:22528
	ds_read_b128 v[232:235], v181 offset:23552
	global_load_lds_dwordx4 v[168:169], off
	s_add_i32 m0, s97, 0x2000
	s_add_u32 vcc_lo, s46, 0x80000
	v_lshl_add_u64 v[176:177], s[46:47], 0, v[144:145]
	s_addc_u32 vcc_hi, s47, 0
	s_add_i32 s97, s67, s2
	global_load_lds_dwordx4 v[176:177], off
	v_lshl_add_u64 v[184:185], vcc, 0, v[148:149]
	s_mov_b32 m0, s97
	s_nop 0
	global_load_lds_dwordx4 v[184:185], off
	v_lshl_add_u64 v[184:185], vcc, 0, v[144:145]
	s_add_i32 m0, s97, 0x2000
	s_nop 0
	global_load_lds_dwordx4 v[184:185], off
	s_waitcnt vmcnt(6)
	s_waitcnt lgkmcnt(0)
	s_barrier
; #define PG8_STAGE(bufoff, gbase, voff) do { _Pragma("unroll") for (int _i = 0; _i < 2; ++_i) \
;         __builtin_amdgcn_global_load_lds((const unsigned*)((const char*)(gbase) + (voff)[_i]), (LAS unsigned*)(lds + (bufoff) + ldsw + _i * 8192), 16, 0, 0); } while (0)
; #define PG8_LDA(dst, b, h) do { _Pragma("unroll") for (int m = 0; m < 4; ++m) _Pragma("unroll") for (int k = 0; k < 2; ++k) dst[m][k] = *(const LAS bf16x8*)(lds + PG8_SA(b, h) + aoff + m * 2048 + k * 1024); } while (0)
; #define PG8_LDB(dst, b, h) do { _Pragma("unroll") for (int n = 0; n < 2; ++n) _Pragma("unroll") for (int k = 0; k < 2; ++k) dst[n][k] = *(const LAS bf16x8*)(lds + PG8_SB(b, h) + boff + n * 2048 + k * 1024); } while (0)
; #define PG8_MMA(ai, bj, At, Bt) do { __builtin_amdgcn_s_setprio(3); _Pragma("unroll") for (int m = 0; m < 4; ++m) _Pragma("unroll") for (int n = 0; n < 2; ++n) _Pragma("unroll") for (int k = 0; k < 2; ++k) \
;         acc[ai][bj][m][n] = __builtin_amdgcn_mfma_f32_16x16x32_bf16(Bt[n][k], At[m][k], acc[ai][bj][m][n], 0, 0, 0); __builtin_amdgcn_s_setprio(0); } while (0)
; #define PG8_WAIT_V(n) asm volatile("s_waitcnt vmcnt(" #n ")" ::: "memory")
; #define PG8_WAIT_L(n) asm volatile("s_waitcnt lgkmcnt(" #n ")" ::: "memory")
; #define PG8_BAR __builtin_amdgcn_s_barrier()
; #define PG8_SCHED __builtin_amdgcn_sched_barrier(0)
; template <class Epi, class Sched>
; __device__ __forceinline__ void gemm_phase(LAS unsigned char* lds, const Gemm g, const Sched& S, const Epi& E, int tid_in) {
;     ...
;             PG8_WAIT_V(6); PG8_WAIT_L(0); PG8_BAR; PG8_MMA(1, 0, At, B0); PG8_MMA(1, 1, At, B1); PG8_BAR; PG8_SCHED;
;             PG8_LDB(B0, 1, 0); PG8_LDB(B1, 1, 1); PG8_SCHED; PG8_LDA(At, 1, 0); PG8_STAGE(PG8_SA(0, 0), a2, voffA); PG8_STAGE(PG8_SA(0, 1), a2 + hstep, voffA);
;             PG8_WAIT_V(8); PG8_WAIT_L(0); PG8_BAR; PG8_MMA(0, 0, At, B0); PG8_MMA(0, 1, At, B1); PG8_BAR; PG8_SCHED;
	s_setprio 3
	s_waitcnt lgkmcnt(0)
	v_mfma_f32_16x16x32_bf16 v[60:63], v[132:135], v[204:207], 0
	v_mfma_f32_16x16x32_bf16 v[56:59], v[140:143], v[204:207], 0
	v_mfma_f32_16x16x32_bf16 v[44:47], v[132:135], v[212:215], 0
	v_mfma_f32_16x16x32_bf16 v[40:43], v[140:143], v[212:215], 0
	v_mfma_f32_16x16x32_bf16 v[28:31], v[132:135], v[220:223], 0
	v_mfma_f32_16x16x32_bf16 v[24:27], v[140:143], v[220:223], 0
	v_mfma_f32_16x16x32_bf16 v[12:15], v[132:135], v[228:231], 0
	v_mfma_f32_16x16x32_bf16 v[8:11], v[140:143], v[228:231], 0
	v_mfma_f32_16x16x32_bf16 v[60:63], v[136:139], v[208:211], v[60:63]
	v_mfma_f32_16x16x32_bf16 v[56:59], v[172:175], v[208:211], v[56:59]
	v_mfma_f32_16x16x32_bf16 v[44:47], v[136:139], v[216:219], v[44:47]
	v_mfma_f32_16x16x32_bf16 v[40:43], v[172:175], v[216:219], v[40:43]
	v_mfma_f32_16x16x32_bf16 v[28:31], v[136:139], v[224:227], v[28:31]
	v_mfma_f32_16x16x32_bf16 v[24:27], v[172:175], v[224:227], v[24:27]
	v_mfma_f32_16x16x32_bf16 v[12:15], v[136:139], v[232:235], v[12:15]
	v_mfma_f32_16x16x32_bf16 v[8:11], v[172:175], v[232:235], v[8:11]
	s_setprio 0
	s_setprio 3
	v_mfma_f32_16x16x32_bf16 v[52:55], v[188:191], v[204:207], 0
	v_mfma_f32_16x16x32_bf16 v[48:51], v[196:199], v[204:207], 0
	v_mfma_f32_16x16x32_bf16 v[36:39], v[188:191], v[212:215], 0
	v_mfma_f32_16x16x32_bf16 v[32:35], v[196:199], v[212:215], 0
	v_mfma_f32_16x16x32_bf16 v[20:23], v[188:191], v[220:223], 0
	v_mfma_f32_16x16x32_bf16 v[16:19], v[196:199], v[220:223], 0
	v_mfma_f32_16x16x32_bf16 v[4:7], v[188:191], v[228:231], 0
	v_mfma_f32_16x16x32_bf16 v[0:3], v[196:199], v[228:231], 0
	v_mfma_f32_16x16x32_bf16 v[52:55], v[192:195], v[208:211], v[52:55]
	v_mfma_f32_16x16x32_bf16 v[48:51], v[200:203], v[208:211], v[48:51]
	v_mfma_f32_16x16x32_bf16 v[36:39], v[192:195], v[216:219], v[36:39]
	v_mfma_f32_16x16x32_bf16 v[32:35], v[200:203], v[216:219], v[32:35]
	v_mfma_f32_16x16x32_bf16 v[20:23], v[192:195], v[224:227], v[20:23]
	v_mfma_f32_16x16x32_bf16 v[16:19], v[200:203], v[224:227], v[16:19]
	v_mfma_f32_16x16x32_bf16 v[4:7], v[192:195], v[232:235], v[4:7]
	v_mfma_f32_16x16x32_bf16 v[0:3], v[200:203], v[232:235], v[0:3]
	s_setprio 0
	s_barrier
	s_add_i32 s97, 0, 0x18000
	v_add_u32_e32 v152, s97, v171
	s_add_i32 vcc_lo, 0, 0x1c000
	ds_read_b128 v[132:135], v152
	ds_read_b128 v[136:139], v152 offset:1024
	ds_read_b128 v[140:143], v152 offset:2048
	ds_read_b128 v[172:175], v152 offset:3072
	v_add_u32_e32 v152, vcc_lo, v171
	ds_read_b128 v[188:191], v152
	ds_read_b128 v[192:195], v152 offset:1024
	ds_read_b128 v[196:199], v152 offset:2048
	ds_read_b128 v[200:203], v152 offset:3072
	s_mov_b32 m0, s60
	v_lshl_add_u64 v[184:185], s[48:49], 0, v[150:151]
	ds_read_b128 v[204:207], v181 offset:32768
	ds_read_b128 v[208:211], v181 offset:33792
	ds_read_b128 v[212:215], v181 offset:34816
	ds_read_b128 v[216:219], v181 offset:35840
	ds_read_b128 v[220:223], v181 offset:36864
	ds_read_b128 v[224:227], v181 offset:37888
	ds_read_b128 v[228:231], v181 offset:38912
	ds_read_b128 v[232:235], v181 offset:39936
	global_load_lds_dwordx4 v[184:185], off
	v_lshl_add_u64 v[184:185], s[48:49], 0, v[146:147]
	s_add_u32 s48, s48, 0x80000
	s_mov_b32 m0, s61
	s_addc_u32 s49, s49, 0
	global_load_lds_dwordx4 v[184:185], off
	v_lshl_add_u64 v[184:185], s[48:49], 0, v[150:151]
	s_mov_b32 m0, s62
	s_nop 0
	global_load_lds_dwordx4 v[184:185], off
	v_lshl_add_u64 v[184:185], s[48:49], 0, v[146:147]
	s_mov_b32 m0, s63
	s_nop 0
	global_load_lds_dwordx4 v[184:185], off
	s_waitcnt vmcnt(8)
	s_waitcnt lgkmcnt(0)
	s_barrier
; #define PG8_STAGE(bufoff, gbase, voff) do { _Pragma("unroll") for (int _i = 0; _i < 2; ++_i) \
;         __builtin_amdgcn_global_load_lds((const unsigned*)((const char*)(gbase) + (voff)[_i]), (LAS unsigned*)(lds + (bufoff) + ldsw + _i * 8192), 16, 0, 0); } while (0)
; #define PG8_LDA(dst, b, h) do { _Pragma("unroll") for (int m = 0; m < 4; ++m) _Pragma("unroll") for (int k = 0; k < 2; ++k) dst[m][k] = *(const LAS bf16x8*)(lds + PG8_SA(b, h) + aoff + m * 2048 + k * 1024); } while (0)
; #define PG8_MMA(ai, bj, At, Bt) do { __builtin_amdgcn_s_setprio(3); _Pragma("unroll") for (int m = 0; m < 4; ++m) _Pragma("unroll") for (int n = 0; n < 2; ++n) _Pragma("unroll") for (int k = 0; k < 2; ++k) \
;         acc[ai][bj][m][n] = __builtin_amdgcn_mfma_f32_16x16x32_bf16(Bt[n][k], At[m][k], acc[ai][bj][m][n], 0, 0, 0); __builtin_amdgcn_s_setprio(0); } while (0)
; #define PG8_WAIT_V(n) asm volatile("s_waitcnt vmcnt(" #n ")" ::: "memory")
; #define PG8_WAIT_L(n) asm volatile("s_waitcnt lgkmcnt(" #n ")" ::: "memory")
; #define PG8_BAR __builtin_amdgcn_s_barrier()
; #define PG8_SCHED __builtin_amdgcn_sched_barrier(0)
; template <class Epi, class Sched>
; __device__ __forceinline__ void gemm_phase(LAS unsigned char* lds, const Gemm g, const Sched& S, const Epi& E, int tid_in) {
;     ...
;             PG8_WAIT_V(8); PG8_WAIT_L(0); PG8_BAR; PG8_MMA(0, 0, At, B0); PG8_MMA(0, 1, At, B1); PG8_BAR; PG8_SCHED;
;             PG8_LDA(At, 1, 1); PG8_STAGE(PG8_SB(1, 0), b3, voffB); PG8_STAGE(PG8_SB(1, 1), b3 + hstep, voffB);
;             PG8_WAIT_V(6); PG8_WAIT_L(0); PG8_BAR; PG8_MMA(1, 0, At, B0); PG8_MMA(1, 1, At, B1); PG8_BAR; PG8_SCHED;
;         }
	s_setprio 3
	s_waitcnt lgkmcnt(0)
	v_mfma_f32_16x16x32_bf16 v[124:127], v[132:135], v[204:207], v[124:127]
	v_mfma_f32_16x16x32_bf16 v[120:123], v[140:143], v[204:207], v[120:123]
	v_mfma_f32_16x16x32_bf16 v[108:111], v[132:135], v[212:215], v[108:111]
	v_mfma_f32_16x16x32_bf16 v[104:107], v[140:143], v[212:215], v[104:107]
	v_mfma_f32_16x16x32_bf16 v[92:95], v[132:135], v[220:223], v[92:95]
	v_mfma_f32_16x16x32_bf16 v[88:91], v[140:143], v[220:223], v[88:91]
	v_mfma_f32_16x16x32_bf16 v[76:79], v[132:135], v[228:231], v[76:79]
	v_mfma_f32_16x16x32_bf16 v[72:75], v[140:143], v[228:231], v[72:75]
	v_mfma_f32_16x16x32_bf16 v[124:127], v[136:139], v[208:211], v[124:127]
	v_mfma_f32_16x16x32_bf16 v[120:123], v[172:175], v[208:211], v[120:123]
	v_mfma_f32_16x16x32_bf16 v[108:111], v[136:139], v[216:219], v[108:111]
	v_mfma_f32_16x16x32_bf16 v[104:107], v[172:175], v[216:219], v[104:107]
	v_mfma_f32_16x16x32_bf16 v[92:95], v[136:139], v[224:227], v[92:95]
	v_mfma_f32_16x16x32_bf16 v[88:91], v[172:175], v[224:227], v[88:91]
	v_mfma_f32_16x16x32_bf16 v[76:79], v[136:139], v[232:235], v[76:79]
	v_mfma_f32_16x16x32_bf16 v[72:75], v[172:175], v[232:235], v[72:75]
	s_setprio 0
	s_setprio 3
	v_mfma_f32_16x16x32_bf16 v[116:119], v[188:191], v[204:207], v[116:119]
	v_mfma_f32_16x16x32_bf16 v[112:115], v[196:199], v[204:207], v[112:115]
	v_mfma_f32_16x16x32_bf16 v[100:103], v[188:191], v[212:215], v[100:103]
	v_mfma_f32_16x16x32_bf16 v[96:99], v[196:199], v[212:215], v[96:99]
	v_mfma_f32_16x16x32_bf16 v[84:87], v[188:191], v[220:223], v[84:87]
	v_mfma_f32_16x16x32_bf16 v[80:83], v[196:199], v[220:223], v[80:83]
	v_mfma_f32_16x16x32_bf16 v[68:71], v[188:191], v[228:231], v[68:71]
	v_mfma_f32_16x16x32_bf16 v[64:67], v[196:199], v[228:231], v[64:67]
	v_mfma_f32_16x16x32_bf16 v[116:119], v[192:195], v[208:211], v[116:119]
	v_mfma_f32_16x16x32_bf16 v[112:115], v[200:203], v[208:211], v[112:115]
	v_mfma_f32_16x16x32_bf16 v[100:103], v[192:195], v[216:219], v[100:103]
	v_mfma_f32_16x16x32_bf16 v[96:99], v[200:203], v[216:219], v[96:99]
	v_mfma_f32_16x16x32_bf16 v[84:87], v[192:195], v[224:227], v[84:87]
	v_mfma_f32_16x16x32_bf16 v[80:83], v[200:203], v[224:227], v[80:83]
	v_mfma_f32_16x16x32_bf16 v[68:71], v[192:195], v[232:235], v[68:71]
	v_mfma_f32_16x16x32_bf16 v[64:67], v[200:203], v[232:235], v[64:67]
	s_setprio 0
	s_barrier
	s_add_i32 s48, s97, s2
	v_lshl_add_u64 v[168:169], v[168:169], 0, s[10:11]
	s_mov_b32 m0, s48
	ds_read_b128 v[204:207], v181 offset:49152
	ds_read_b128 v[208:211], v181 offset:50176
	ds_read_b128 v[212:215], v181 offset:51200
	ds_read_b128 v[216:219], v181 offset:52224
	ds_read_b128 v[220:223], v181 offset:53248
	ds_read_b128 v[224:227], v181 offset:54272
	ds_read_b128 v[228:231], v181 offset:55296
	ds_read_b128 v[232:235], v181 offset:56320
	global_load_lds_dwordx4 v[168:169], off
	s_add_i32 m0, s48, 0x2000
	s_add_u32 s46, s46, 0x80080
	v_lshl_add_u64 v[168:169], v[176:177], 0, s[10:11]
	s_addc_u32 s47, s47, 0
	s_add_i32 s48, vcc_lo, s2
	global_load_lds_dwordx4 v[168:169], off
	v_lshl_add_u64 v[168:169], s[46:47], 0, v[148:149]
	s_mov_b32 m0, s48
	s_nop 0
	global_load_lds_dwordx4 v[168:169], off
	v_lshl_add_u64 v[168:169], s[46:47], 0, v[144:145]
	s_add_i32 m0, s48, 0x2000
	s_nop 0
	global_load_lds_dwordx4 v[168:169], off
	s_waitcnt vmcnt(6)
	s_waitcnt lgkmcnt(0)
	s_barrier
	s_setprio 3
	s_waitcnt lgkmcnt(0)
	v_mfma_f32_16x16x32_bf16 v[60:63], v[132:135], v[204:207], v[60:63]
	v_mfma_f32_16x16x32_bf16 v[56:59], v[140:143], v[204:207], v[56:59]
	v_mfma_f32_16x16x32_bf16 v[44:47], v[132:135], v[212:215], v[44:47]
	v_mfma_f32_16x16x32_bf16 v[40:43], v[140:143], v[212:215], v[40:43]
	v_mfma_f32_16x16x32_bf16 v[28:31], v[132:135], v[220:223], v[28:31]
	v_mfma_f32_16x16x32_bf16 v[24:27], v[140:143], v[220:223], v[24:27]
	v_mfma_f32_16x16x32_bf16 v[12:15], v[132:135], v[228:231], v[12:15]
	v_mfma_f32_16x16x32_bf16 v[8:11], v[140:143], v[228:231], v[8:11]
	v_mfma_f32_16x16x32_bf16 v[60:63], v[136:139], v[208:211], v[60:63]
	v_mfma_f32_16x16x32_bf16 v[56:59], v[172:175], v[208:211], v[56:59]
	v_mfma_f32_16x16x32_bf16 v[44:47], v[136:139], v[216:219], v[44:47]
	v_mfma_f32_16x16x32_bf16 v[40:43], v[172:175], v[216:219], v[40:43]
	v_mfma_f32_16x16x32_bf16 v[28:31], v[136:139], v[224:227], v[28:31]
	v_mfma_f32_16x16x32_bf16 v[24:27], v[172:175], v[224:227], v[24:27]
	v_mfma_f32_16x16x32_bf16 v[12:15], v[136:139], v[232:235], v[12:15]
	v_mfma_f32_16x16x32_bf16 v[8:11], v[172:175], v[232:235], v[8:11]
	s_setprio 0
	s_setprio 3
	v_mfma_f32_16x16x32_bf16 v[52:55], v[188:191], v[204:207], v[52:55]
	v_mfma_f32_16x16x32_bf16 v[48:51], v[196:199], v[204:207], v[48:51]
	v_mfma_f32_16x16x32_bf16 v[36:39], v[188:191], v[212:215], v[36:39]
	v_mfma_f32_16x16x32_bf16 v[32:35], v[196:199], v[212:215], v[32:35]
	v_mfma_f32_16x16x32_bf16 v[20:23], v[188:191], v[220:223], v[20:23]
	v_mfma_f32_16x16x32_bf16 v[16:19], v[196:199], v[220:223], v[16:19]
	v_mfma_f32_16x16x32_bf16 v[4:7], v[188:191], v[228:231], v[4:7]
	v_mfma_f32_16x16x32_bf16 v[0:3], v[196:199], v[228:231], v[0:3]
	v_mfma_f32_16x16x32_bf16 v[52:55], v[192:195], v[208:211], v[52:55]
	v_mfma_f32_16x16x32_bf16 v[48:51], v[200:203], v[208:211], v[48:51]
	v_mfma_f32_16x16x32_bf16 v[36:39], v[192:195], v[216:219], v[36:39]
	v_mfma_f32_16x16x32_bf16 v[32:35], v[200:203], v[216:219], v[32:35]
	v_mfma_f32_16x16x32_bf16 v[20:23], v[192:195], v[224:227], v[20:23]
	v_mfma_f32_16x16x32_bf16 v[16:19], v[200:203], v[224:227], v[16:19]
	v_mfma_f32_16x16x32_bf16 v[4:7], v[192:195], v[232:235], v[4:7]
	v_mfma_f32_16x16x32_bf16 v[0:3], v[200:203], v[232:235], v[0:3]
	s_setprio 0
	s_barrier
	s_add_i32 s96, s96, 2
	s_add_u32 s44, s44, 0x100
	s_addc_u32 s45, s45, 0
	s_cmp_gt_u32 s96, 29
	s_cbranch_scc0 .LBB0_102
	s_branch .Lpeel_exit_0

; #define PG8_BAR __builtin_amdgcn_s_barrier()
; template <class Epi, class Sched>
; __device__ __forceinline__ void gemm_phase(LAS unsigned char* lds, const Gemm g, const Sched& S, const Epi& E, int tid_in) {
;     ...
;         if (wr == 0) PG8_BAR;
.Lpeel_exit_0:
	s_and_b64 vcc, exec, s[14:15]
	s_cbranch_vccz .LBB0_107
	s_barrier
	v_lshl_add_u32 v168, s40, 8, v155
	s_cmp_gt_i32 s38, 4
	s_mov_b64 s[40:41], -1
	s_cbranch_scc1 .LBB0_108

;     __device__ bool next(int i, Unit& u) const { if (!b.next(i >> 1, u)) return false; u.half = i & 1; u.koff = (i & 1) * kbytes; return true; }
; #define PG8_STAGE(bufoff, gbase, voff) do { _Pragma("unroll") for (int _i = 0; _i < 2; ++_i) \
;         __builtin_amdgcn_global_load_lds((const unsigned*)((const char*)(gbase) + (voff)[_i]), (LAS unsigned*)(lds + (bufoff) + ldsw + _i * 8192), 16, 0, 0); } while (0)
; #define PG8_LDA(dst, b, h) do { _Pragma("unroll") for (int m = 0; m < 4; ++m) _Pragma("unroll") for (int k = 0; k < 2; ++k) dst[m][k] = *(const LAS bf16x8*)(lds + PG8_SA(b, h) + aoff + m * 2048 + k * 1024); } while (0)
; #define PG8_LDB(dst, b, h) do { _Pragma("unroll") for (int n = 0; n < 2; ++n) _Pragma("unroll") for (int k = 0; k < 2; ++k) dst[n][k] = *(const LAS bf16x8*)(lds + PG8_SB(b, h) + boff + n * 2048 + k * 1024); } while (0)
; #define PG8_WAIT_V(n) asm volatile("s_waitcnt vmcnt(" #n ")" ::: "memory")
; #define PG8_WAIT_L(n) asm volatile("s_waitcnt lgkmcnt(" #n ")" ::: "memory")
; #define PG8_BAR __builtin_amdgcn_s_barrier()
; #define PG8_SCHED __builtin_amdgcn_sched_barrier(0)
; template <class Epi, class Sched>
; __device__ __forceinline__ void gemm_phase(LAS unsigned char* lds, const Gemm g, const Sched& S, const Epi& E, int tid_in) {
;     ...
;         const bool has_next = S.next(ui + 1, nxt);
;         const char* nA = has_next ? (const char*)g.A + (size_t)nxt.pm * tstep + nxt.koff : cA; const char* nB = has_next ? (const char*)g.Bt + (size_t)nxt.pn * tstep + nxt.koff : cB;
;         for (int t = 0; t < nt; t += 2) {
;             const bool last = (t == nt - 2);
;             const char* a1 = cA + (size_t)(t + 1) * kstep;
;             const char* a2 = last ? nA : cA + (size_t)(t + 2) * kstep; const char* b2 = last ? nB : cB + (size_t)(t + 2) * kstep;
;             const char* a3 = a2 + kstep; const char* b3 = b2 + kstep;
;             PG8_LDB(B0, 0, 0); PG8_LDB(B1, 0, 1); PG8_SCHED; PG8_LDA(At, 0, 0); PG8_STAGE(PG8_SA(1, 0), a1, voffA); PG8_STAGE(PG8_SA(1, 1), a1 + hstep, voffA);
;             PG8_WAIT_V(8); PG8_WAIT_L(0); PG8_BAR; PG8_MMA(0, 0, At, B0); PG8_MMA(0, 1, At, B1); PG8_BAR; PG8_SCHED;
;             PG8_LDA(At, 0, 1); PG8_STAGE(PG8_SB(0, 0), b2, voffB); PG8_STAGE(PG8_SB(0, 1), b2 + hstep, voffB);
;             PG8_WAIT_V(6); PG8_WAIT_L(0); PG8_BAR; PG8_MMA(1, 0, At, B0); PG8_MMA(1, 1, At, B1); PG8_BAR; PG8_SCHED;
.LBB0_619:
	s_ashr_i32 s25, s24, 31
	s_lshl_b64 s[26:27], s[24:25], 20
	s_add_u32 s26, s8, s26
	s_addc_u32 s27, s9, s27
	s_and_b64 s[28:29], s[4:5], exec
	s_cselect_b32 s25, s27, s35
	s_cselect_b32 s31, s26, s34
	s_ashr_i32 s23, s22, 31
	s_lshl_b64 s[28:29], s[22:23], 20
	s_add_u32 s28, s68, s28
	s_addc_u32 s29, s69, s29
	s_and_b64 s[38:39], s[4:5], exec
	s_cselect_b32 s23, s29, s37
	s_cselect_b32 s49, s28, s36
	s_add_u32 s51, s36, 0x100
	s_addc_u32 s70, s37, 0
	v_lshl_add_u64 v[144:145], s[34:35], 0, v[136:137]
	v_lshl_add_u64 v[146:147], s[34:35], 0, v[138:139]
	s_mov_b32 s71, -2
	s_mov_b64 s[36:37], 0
	s_waitcnt lgkmcnt(0)
	ds_read_b128 v[156:159], v151
	ds_read_b128 v[160:163], v151 offset:1024
	ds_read_b128 v[164:167], v151 offset:2048
	ds_read_b128 v[168:171], v151 offset:3072
	ds_read_b128 v[172:175], v152
	ds_read_b128 v[176:179], v152 offset:1024
	ds_read_b128 v[180:183], v152 offset:2048
	ds_read_b128 v[188:191], v152 offset:3072
	s_add_u32 s38, s34, s36
	s_addc_u32 s39, s35, s37
	s_add_u32 s40, s38, 0x100
	s_addc_u32 s41, s39, 0
	s_add_u32 s38, s51, s36
	s_addc_u32 s39, s70, s37
	s_cmpk_eq_i32 s36, 0xf00
	s_cselect_b32 s39, s23, s39
	s_cselect_b32 s38, s49, s38
	s_cselect_b32 s41, s25, s41
	s_cselect_b32 s40, s31, s40
	v_lshl_add_u64 v[184:185], v[144:145], 0, s[36:37]
	v_lshl_add_u64 v[224:225], v[184:185], 0, s[16:17]
	s_add_i32 m0, s3, 0x8000
	ds_read_b128 v[192:195], v153
	ds_read_b128 v[196:199], v153 offset:1024
	ds_read_b128 v[200:203], v153 offset:2048
	ds_read_b128 v[204:207], v153 offset:3072
	ds_read_b128 v[208:211], v153 offset:4096
	ds_read_b128 v[212:215], v153 offset:5120
	ds_read_b128 v[216:219], v153 offset:6144
	ds_read_b128 v[220:223], v153 offset:7168
	global_load_lds_dwordx4 v[224:225], off
	v_lshl_add_u64 v[224:225], v[146:147], 0, s[36:37]
	v_lshl_add_u64 v[226:227], v[224:225], 0, s[16:17]
	s_add_i32 m0, s3, 0xa000
	v_lshl_add_u64 v[184:185], v[184:185], 0, s[18:19]
	global_load_lds_dwordx4 v[226:227], off
	s_add_i32 m0, s3, 0xc000
	s_nop 0
	global_load_lds_dwordx4 v[184:185], off
	v_lshl_add_u64 v[184:185], v[224:225], 0, s[18:19]
	s_add_i32 m0, s3, 0xe000
	s_nop 0
	global_load_lds_dwordx4 v[184:185], off
	s_waitcnt vmcnt(8)
	s_waitcnt lgkmcnt(0)
	s_barrier
	s_setprio 3
	s_waitcnt lgkmcnt(0)
	v_mfma_f32_16x16x32_bf16 v[124:127], v[156:159], v[192:195], 0
	v_mfma_f32_16x16x32_bf16 v[120:123], v[164:167], v[192:195], 0
	v_mfma_f32_16x16x32_bf16 v[108:111], v[156:159], v[200:203], 0
	v_mfma_f32_16x16x32_bf16 v[104:107], v[164:167], v[200:203], 0
	v_mfma_f32_16x16x32_bf16 v[92:95], v[156:159], v[208:211], 0
	v_mfma_f32_16x16x32_bf16 v[88:91], v[164:167], v[208:211], 0
	v_mfma_f32_16x16x32_bf16 v[76:79], v[156:159], v[216:219], 0
	v_mfma_f32_16x16x32_bf16 v[72:75], v[164:167], v[216:219], 0
	v_mfma_f32_16x16x32_bf16 v[124:127], v[160:163], v[196:199], v[124:127]
	v_mfma_f32_16x16x32_bf16 v[120:123], v[168:171], v[196:199], v[120:123]
	v_mfma_f32_16x16x32_bf16 v[108:111], v[160:163], v[204:207], v[108:111]
	v_mfma_f32_16x16x32_bf16 v[104:107], v[168:171], v[204:207], v[104:107]
	v_mfma_f32_16x16x32_bf16 v[92:95], v[160:163], v[212:215], v[92:95]
	v_mfma_f32_16x16x32_bf16 v[88:91], v[168:171], v[212:215], v[88:91]
	v_mfma_f32_16x16x32_bf16 v[76:79], v[160:163], v[220:223], v[76:79]
	v_mfma_f32_16x16x32_bf16 v[72:75], v[168:171], v[220:223], v[72:75]
	s_setprio 0
	s_setprio 3
	v_mfma_f32_16x16x32_bf16 v[116:119], v[172:175], v[192:195], 0
	v_mfma_f32_16x16x32_bf16 v[112:115], v[180:183], v[192:195], 0
	v_mfma_f32_16x16x32_bf16 v[100:103], v[172:175], v[200:203], 0
	v_mfma_f32_16x16x32_bf16 v[96:99], v[180:183], v[200:203], 0
	v_mfma_f32_16x16x32_bf16 v[84:87], v[172:175], v[208:211], 0
	v_mfma_f32_16x16x32_bf16 v[80:83], v[180:183], v[208:211], 0
	v_mfma_f32_16x16x32_bf16 v[68:71], v[172:175], v[216:219], 0
	v_mfma_f32_16x16x32_bf16 v[64:67], v[180:183], v[216:219], 0
	v_mfma_f32_16x16x32_bf16 v[116:119], v[176:179], v[196:199], v[116:119]
	v_mfma_f32_16x16x32_bf16 v[112:115], v[188:191], v[196:199], v[112:115]
	v_mfma_f32_16x16x32_bf16 v[100:103], v[176:179], v[204:207], v[100:103]
	v_mfma_f32_16x16x32_bf16 v[96:99], v[188:191], v[204:207], v[96:99]
	v_mfma_f32_16x16x32_bf16 v[84:87], v[176:179], v[212:215], v[84:87]
	v_mfma_f32_16x16x32_bf16 v[80:83], v[188:191], v[212:215], v[80:83]
	v_mfma_f32_16x16x32_bf16 v[68:71], v[176:179], v[220:223], v[68:71]
	v_mfma_f32_16x16x32_bf16 v[64:67], v[188:191], v[220:223], v[64:67]
	s_setprio 0
	s_barrier
	s_add_i32 s72, s46, s2
	v_lshl_add_u64 v[184:185], s[38:39], 0, v[130:131]
	s_mov_b32 m0, s72
	ds_read_b128 v[192:195], v153 offset:16384
	ds_read_b128 v[196:199], v153 offset:17408
	ds_read_b128 v[200:203], v153 offset:18432
	ds_read_b128 v[204:207], v153 offset:19456
	ds_read_b128 v[208:211], v153 offset:20480
	ds_read_b128 v[212:215], v153 offset:21504
	ds_read_b128 v[216:219], v153 offset:22528
	ds_read_b128 v[220:223], v153 offset:23552
	global_load_lds_dwordx4 v[184:185], off
	s_add_i32 m0, s72, 0x2000
	s_add_u32 s72, s38, 0x80000
	v_lshl_add_u64 v[224:225], s[38:39], 0, v[134:135]
	s_addc_u32 s73, s39, 0
	s_add_i32 s74, s47, s2
	global_load_lds_dwordx4 v[224:225], off
	v_lshl_add_u64 v[226:227], s[72:73], 0, v[130:131]
	s_mov_b32 m0, s74
	s_nop 0
	global_load_lds_dwordx4 v[226:227], off
	v_lshl_add_u64 v[226:227], s[72:73], 0, v[134:135]
	s_add_i32 m0, s74, 0x2000
	s_nop 0
	global_load_lds_dwordx4 v[226:227], off
	s_waitcnt vmcnt(6)
	s_waitcnt lgkmcnt(0)
	s_barrier
; #define PG8_STAGE(bufoff, gbase, voff) do { _Pragma("unroll") for (int _i = 0; _i < 2; ++_i) \
;         __builtin_amdgcn_global_load_lds((const unsigned*)((const char*)(gbase) + (voff)[_i]), (LAS unsigned*)(lds + (bufoff) + ldsw + _i * 8192), 16, 0, 0); } while (0)
; #define PG8_LDA(dst, b, h) do { _Pragma("unroll") for (int m = 0; m < 4; ++m) _Pragma("unroll") for (int k = 0; k < 2; ++k) dst[m][k] = *(const LAS bf16x8*)(lds + PG8_SA(b, h) + aoff + m * 2048 + k * 1024); } while (0)
; #define PG8_LDB(dst, b, h) do { _Pragma("unroll") for (int n = 0; n < 2; ++n) _Pragma("unroll") for (int k = 0; k < 2; ++k) dst[n][k] = *(const LAS bf16x8*)(lds + PG8_SB(b, h) + boff + n * 2048 + k * 1024); } while (0)
; #define PG8_MMA(ai, bj, At, Bt) do { __builtin_amdgcn_s_setprio(3); _Pragma("unroll") for (int m = 0; m < 4; ++m) _Pragma("unroll") for (int n = 0; n < 2; ++n) _Pragma("unroll") for (int k = 0; k < 2; ++k) \
;         acc[ai][bj][m][n] = __builtin_amdgcn_mfma_f32_16x16x32_bf16(Bt[n][k], At[m][k], acc[ai][bj][m][n], 0, 0, 0); __builtin_amdgcn_s_setprio(0); } while (0)
; #define PG8_WAIT_V(n) asm volatile("s_waitcnt vmcnt(" #n ")" ::: "memory")
; #define PG8_WAIT_L(n) asm volatile("s_waitcnt lgkmcnt(" #n ")" ::: "memory")
; #define PG8_BAR __builtin_amdgcn_s_barrier()
; #define PG8_SCHED __builtin_amdgcn_sched_barrier(0)
; template <class Epi, class Sched>
; __device__ __forceinline__ void gemm_phase(LAS unsigned char* lds, const Gemm g, const Sched& S, const Epi& E, int tid_in) {
;     ...
;             PG8_WAIT_V(6); PG8_WAIT_L(0); PG8_BAR; PG8_MMA(1, 0, At, B0); PG8_MMA(1, 1, At, B1); PG8_BAR; PG8_SCHED;
;             PG8_LDB(B0, 1, 0); PG8_LDB(B1, 1, 1); PG8_SCHED; PG8_LDA(At, 1, 0); PG8_STAGE(PG8_SA(0, 0), a2, voffA); PG8_STAGE(PG8_SA(0, 1), a2 + hstep, voffA);
;             PG8_WAIT_V(8); PG8_WAIT_L(0); PG8_BAR; PG8_MMA(0, 0, At, B0); PG8_MMA(0, 1, At, B1); PG8_BAR; PG8_SCHED;
	s_setprio 3
	s_waitcnt lgkmcnt(0)
	v_mfma_f32_16x16x32_bf16 v[60:63], v[156:159], v[192:195], 0
	v_mfma_f32_16x16x32_bf16 v[56:59], v[164:167], v[192:195], 0
	v_mfma_f32_16x16x32_bf16 v[44:47], v[156:159], v[200:203], 0
	v_mfma_f32_16x16x32_bf16 v[40:43], v[164:167], v[200:203], 0
	v_mfma_f32_16x16x32_bf16 v[28:31], v[156:159], v[208:211], 0
	v_mfma_f32_16x16x32_bf16 v[24:27], v[164:167], v[208:211], 0
	v_mfma_f32_16x16x32_bf16 v[12:15], v[156:159], v[216:219], 0
	v_mfma_f32_16x16x32_bf16 v[8:11], v[164:167], v[216:219], 0
	v_mfma_f32_16x16x32_bf16 v[60:63], v[160:163], v[196:199], v[60:63]
	v_mfma_f32_16x16x32_bf16 v[56:59], v[168:171], v[196:199], v[56:59]
	v_mfma_f32_16x16x32_bf16 v[44:47], v[160:163], v[204:207], v[44:47]
	v_mfma_f32_16x16x32_bf16 v[40:43], v[168:171], v[204:207], v[40:43]
	v_mfma_f32_16x16x32_bf16 v[28:31], v[160:163], v[212:215], v[28:31]
	v_mfma_f32_16x16x32_bf16 v[24:27], v[168:171], v[212:215], v[24:27]
	v_mfma_f32_16x16x32_bf16 v[12:15], v[160:163], v[220:223], v[12:15]
	v_mfma_f32_16x16x32_bf16 v[8:11], v[168:171], v[220:223], v[8:11]
	s_setprio 0
	s_setprio 3
	v_mfma_f32_16x16x32_bf16 v[52:55], v[172:175], v[192:195], 0
	v_mfma_f32_16x16x32_bf16 v[48:51], v[180:183], v[192:195], 0
	v_mfma_f32_16x16x32_bf16 v[36:39], v[172:175], v[200:203], 0
	v_mfma_f32_16x16x32_bf16 v[32:35], v[180:183], v[200:203], 0
	v_mfma_f32_16x16x32_bf16 v[20:23], v[172:175], v[208:211], 0
	v_mfma_f32_16x16x32_bf16 v[16:19], v[180:183], v[208:211], 0
	v_mfma_f32_16x16x32_bf16 v[4:7], v[172:175], v[216:219], 0
	v_mfma_f32_16x16x32_bf16 v[0:3], v[180:183], v[216:219], 0
	v_mfma_f32_16x16x32_bf16 v[52:55], v[176:179], v[196:199], v[52:55]
	v_mfma_f32_16x16x32_bf16 v[48:51], v[188:191], v[196:199], v[48:51]
	v_mfma_f32_16x16x32_bf16 v[36:39], v[176:179], v[204:207], v[36:39]
	v_mfma_f32_16x16x32_bf16 v[32:35], v[188:191], v[204:207], v[32:35]
	v_mfma_f32_16x16x32_bf16 v[20:23], v[176:179], v[212:215], v[20:23]
	v_mfma_f32_16x16x32_bf16 v[16:19], v[188:191], v[212:215], v[16:19]
	v_mfma_f32_16x16x32_bf16 v[4:7], v[176:179], v[220:223], v[4:7]
	v_mfma_f32_16x16x32_bf16 v[0:3], v[188:191], v[220:223], v[0:3]
	s_setprio 0
	s_barrier
	s_add_i32 s72, 0, 0x18000
	v_add_u32_e32 v155, s72, v149
	s_add_i32 s73, 0, 0x1c000
	ds_read_b128 v[156:159], v155
	ds_read_b128 v[160:163], v155 offset:1024
	ds_read_b128 v[164:167], v155 offset:2048
	ds_read_b128 v[168:171], v155 offset:3072
	v_add_u32_e32 v155, s73, v149
	ds_read_b128 v[172:175], v155
	ds_read_b128 v[176:179], v155 offset:1024
	ds_read_b128 v[180:183], v155 offset:2048
	ds_read_b128 v[188:191], v155 offset:3072
	s_mov_b32 m0, s3
	v_lshl_add_u64 v[226:227], s[40:41], 0, v[128:129]
	ds_read_b128 v[192:195], v153 offset:32768
	ds_read_b128 v[196:199], v153 offset:33792
	ds_read_b128 v[200:203], v153 offset:34816
	ds_read_b128 v[204:207], v153 offset:35840
	ds_read_b128 v[208:211], v153 offset:36864
	ds_read_b128 v[212:215], v153 offset:37888
	ds_read_b128 v[216:219], v153 offset:38912
	ds_read_b128 v[220:223], v153 offset:39936
	global_load_lds_dwordx4 v[226:227], off
	v_lshl_add_u64 v[226:227], s[40:41], 0, v[132:133]
	s_add_u32 s40, s40, 0x80000
	s_mov_b32 m0, s42
	s_addc_u32 s41, s41, 0
	global_load_lds_dwordx4 v[226:227], off
	v_lshl_add_u64 v[226:227], s[40:41], 0, v[128:129]
	s_mov_b32 m0, s43
	s_nop 0
	global_load_lds_dwordx4 v[226:227], off
	v_lshl_add_u64 v[226:227], s[40:41], 0, v[132:133]
	s_mov_b32 m0, s44
	s_nop 0
	global_load_lds_dwordx4 v[226:227], off
	s_waitcnt vmcnt(8)
	s_waitcnt lgkmcnt(0)
	s_barrier
; #define PG8_STAGE(bufoff, gbase, voff) do { _Pragma("unroll") for (int _i = 0; _i < 2; ++_i) \
;         __builtin_amdgcn_global_load_lds((const unsigned*)((const char*)(gbase) + (voff)[_i]), (LAS unsigned*)(lds + (bufoff) + ldsw + _i * 8192), 16, 0, 0); } while (0)
; #define PG8_LDA(dst, b, h) do { _Pragma("unroll") for (int m = 0; m < 4; ++m) _Pragma("unroll") for (int k = 0; k < 2; ++k) dst[m][k] = *(const LAS bf16x8*)(lds + PG8_SA(b, h) + aoff + m * 2048 + k * 1024); } while (0)
; #define PG8_MMA(ai, bj, At, Bt) do { __builtin_amdgcn_s_setprio(3); _Pragma("unroll") for (int m = 0; m < 4; ++m) _Pragma("unroll") for (int n = 0; n < 2; ++n) _Pragma("unroll") for (int k = 0; k < 2; ++k) \
;         acc[ai][bj][m][n] = __builtin_amdgcn_mfma_f32_16x16x32_bf16(Bt[n][k], At[m][k], acc[ai][bj][m][n], 0, 0, 0); __builtin_amdgcn_s_setprio(0); } while (0)
; #define PG8_WAIT_V(n) asm volatile("s_waitcnt vmcnt(" #n ")" ::: "memory")
; #define PG8_WAIT_L(n) asm volatile("s_waitcnt lgkmcnt(" #n ")" ::: "memory")
; #define PG8_BAR __builtin_amdgcn_s_barrier()
; #define PG8_SCHED __builtin_amdgcn_sched_barrier(0)
; template <class Epi, class Sched>
; __device__ __forceinline__ void gemm_phase(LAS unsigned char* lds, const Gemm g, const Sched& S, const Epi& E, int tid_in) {
;     ...
;             PG8_WAIT_V(8); PG8_WAIT_L(0); PG8_BAR; PG8_MMA(0, 0, At, B0); PG8_MMA(0, 1, At, B1); PG8_BAR; PG8_SCHED;
;             PG8_LDA(At, 1, 1); PG8_STAGE(PG8_SB(1, 0), b3, voffB); PG8_STAGE(PG8_SB(1, 1), b3 + hstep, voffB);
;             PG8_WAIT_V(6); PG8_WAIT_L(0); PG8_BAR; PG8_MMA(1, 0, At, B0); PG8_MMA(1, 1, At, B1); PG8_BAR; PG8_SCHED;
;         }
	s_setprio 3
	s_waitcnt lgkmcnt(0)
	v_mfma_f32_16x16x32_bf16 v[124:127], v[156:159], v[192:195], v[124:127]
	v_mfma_f32_16x16x32_bf16 v[120:123], v[164:167], v[192:195], v[120:123]
	v_mfma_f32_16x16x32_bf16 v[108:111], v[156:159], v[200:203], v[108:111]
	v_mfma_f32_16x16x32_bf16 v[104:107], v[164:167], v[200:203], v[104:107]
	v_mfma_f32_16x16x32_bf16 v[92:95], v[156:159], v[208:211], v[92:95]
	v_mfma_f32_16x16x32_bf16 v[88:91], v[164:167], v[208:211], v[88:91]
	v_mfma_f32_16x16x32_bf16 v[76:79], v[156:159], v[216:219], v[76:79]
	v_mfma_f32_16x16x32_bf16 v[72:75], v[164:167], v[216:219], v[72:75]
	v_mfma_f32_16x16x32_bf16 v[124:127], v[160:163], v[196:199], v[124:127]
	v_mfma_f32_16x16x32_bf16 v[120:123], v[168:171], v[196:199], v[120:123]
	v_mfma_f32_16x16x32_bf16 v[108:111], v[160:163], v[204:207], v[108:111]
	v_mfma_f32_16x16x32_bf16 v[104:107], v[168:171], v[204:207], v[104:107]
	v_mfma_f32_16x16x32_bf16 v[92:95], v[160:163], v[212:215], v[92:95]
	v_mfma_f32_16x16x32_bf16 v[88:91], v[168:171], v[212:215], v[88:91]
	v_mfma_f32_16x16x32_bf16 v[76:79], v[160:163], v[220:223], v[76:79]
	v_mfma_f32_16x16x32_bf16 v[72:75], v[168:171], v[220:223], v[72:75]
	s_setprio 0
	s_setprio 3
	v_mfma_f32_16x16x32_bf16 v[116:119], v[172:175], v[192:195], v[116:119]
	v_mfma_f32_16x16x32_bf16 v[112:115], v[180:183], v[192:195], v[112:115]
	v_mfma_f32_16x16x32_bf16 v[100:103], v[172:175], v[200:203], v[100:103]
	v_mfma_f32_16x16x32_bf16 v[96:99], v[180:183], v[200:203], v[96:99]
	v_mfma_f32_16x16x32_bf16 v[84:87], v[172:175], v[208:211], v[84:87]
	v_mfma_f32_16x16x32_bf16 v[80:83], v[180:183], v[208:211], v[80:83]
	v_mfma_f32_16x16x32_bf16 v[68:71], v[172:175], v[216:219], v[68:71]
	v_mfma_f32_16x16x32_bf16 v[64:67], v[180:183], v[216:219], v[64:67]
	v_mfma_f32_16x16x32_bf16 v[116:119], v[176:179], v[196:199], v[116:119]
	v_mfma_f32_16x16x32_bf16 v[112:115], v[188:191], v[196:199], v[112:115]
	v_mfma_f32_16x16x32_bf16 v[100:103], v[176:179], v[204:207], v[100:103]
	v_mfma_f32_16x16x32_bf16 v[96:99], v[188:191], v[204:207], v[96:99]
	v_mfma_f32_16x16x32_bf16 v[84:87], v[176:179], v[212:215], v[84:87]
	v_mfma_f32_16x16x32_bf16 v[80:83], v[188:191], v[212:215], v[80:83]
	v_mfma_f32_16x16x32_bf16 v[68:71], v[176:179], v[220:223], v[68:71]
	v_mfma_f32_16x16x32_bf16 v[64:67], v[188:191], v[220:223], v[64:67]
	s_setprio 0
	s_barrier
	s_add_i32 s40, s72, s2
	v_lshl_add_u64 v[184:185], v[184:185], 0, s[16:17]
	s_mov_b32 m0, s40
	ds_read_b128 v[192:195], v153 offset:49152
	ds_read_b128 v[196:199], v153 offset:50176
	ds_read_b128 v[200:203], v153 offset:51200
	ds_read_b128 v[204:207], v153 offset:52224
	ds_read_b128 v[208:211], v153 offset:53248
	ds_read_b128 v[212:215], v153 offset:54272
	ds_read_b128 v[216:219], v153 offset:55296
	ds_read_b128 v[220:223], v153 offset:56320
	global_load_lds_dwordx4 v[184:185], off
	s_add_i32 m0, s40, 0x2000
	s_add_u32 s38, s38, 0x80080
	v_lshl_add_u64 v[184:185], v[224:225], 0, s[16:17]
	s_addc_u32 s39, s39, 0
	s_add_i32 s40, s73, s2
	global_load_lds_dwordx4 v[184:185], off
	v_lshl_add_u64 v[184:185], s[38:39], 0, v[130:131]
	s_mov_b32 m0, s40
	s_nop 0
	global_load_lds_dwordx4 v[184:185], off
	v_lshl_add_u64 v[184:185], s[38:39], 0, v[134:135]
	s_add_i32 m0, s40, 0x2000
	s_nop 0
	global_load_lds_dwordx4 v[184:185], off
	s_waitcnt vmcnt(6)
	s_waitcnt lgkmcnt(0)
	s_barrier
	s_setprio 3
	s_waitcnt lgkmcnt(0)
	v_mfma_f32_16x16x32_bf16 v[60:63], v[156:159], v[192:195], v[60:63]
	v_mfma_f32_16x16x32_bf16 v[56:59], v[164:167], v[192:195], v[56:59]
	v_mfma_f32_16x16x32_bf16 v[44:47], v[156:159], v[200:203], v[44:47]
	v_mfma_f32_16x16x32_bf16 v[40:43], v[164:167], v[200:203], v[40:43]
	v_mfma_f32_16x16x32_bf16 v[28:31], v[156:159], v[208:211], v[28:31]
	v_mfma_f32_16x16x32_bf16 v[24:27], v[164:167], v[208:211], v[24:27]
	v_mfma_f32_16x16x32_bf16 v[12:15], v[156:159], v[216:219], v[12:15]
	v_mfma_f32_16x16x32_bf16 v[8:11], v[164:167], v[216:219], v[8:11]
	v_mfma_f32_16x16x32_bf16 v[60:63], v[160:163], v[196:199], v[60:63]
	v_mfma_f32_16x16x32_bf16 v[56:59], v[168:171], v[196:199], v[56:59]
	v_mfma_f32_16x16x32_bf16 v[44:47], v[160:163], v[204:207], v[44:47]
	v_mfma_f32_16x16x32_bf16 v[40:43], v[168:171], v[204:207], v[40:43]
	v_mfma_f32_16x16x32_bf16 v[28:31], v[160:163], v[212:215], v[28:31]
	v_mfma_f32_16x16x32_bf16 v[24:27], v[168:171], v[212:215], v[24:27]
	v_mfma_f32_16x16x32_bf16 v[12:15], v[160:163], v[220:223], v[12:15]
	v_mfma_f32_16x16x32_bf16 v[8:11], v[168:171], v[220:223], v[8:11]
	s_setprio 0
	s_setprio 3
	v_mfma_f32_16x16x32_bf16 v[52:55], v[172:175], v[192:195], v[52:55]
	v_mfma_f32_16x16x32_bf16 v[48:51], v[180:183], v[192:195], v[48:51]
	v_mfma_f32_16x16x32_bf16 v[36:39], v[172:175], v[200:203], v[36:39]
	v_mfma_f32_16x16x32_bf16 v[32:35], v[180:183], v[200:203], v[32:35]
	v_mfma_f32_16x16x32_bf16 v[20:23], v[172:175], v[208:211], v[20:23]
	v_mfma_f32_16x16x32_bf16 v[16:19], v[180:183], v[208:211], v[16:19]
	v_mfma_f32_16x16x32_bf16 v[4:7], v[172:175], v[216:219], v[4:7]
	v_mfma_f32_16x16x32_bf16 v[0:3], v[180:183], v[216:219], v[0:3]
	v_mfma_f32_16x16x32_bf16 v[52:55], v[176:179], v[196:199], v[52:55]
	v_mfma_f32_16x16x32_bf16 v[48:51], v[188:191], v[196:199], v[48:51]
	v_mfma_f32_16x16x32_bf16 v[36:39], v[176:179], v[204:207], v[36:39]
	v_mfma_f32_16x16x32_bf16 v[32:35], v[188:191], v[204:207], v[32:35]
	v_mfma_f32_16x16x32_bf16 v[20:23], v[176:179], v[212:215], v[20:23]
	v_mfma_f32_16x16x32_bf16 v[16:19], v[188:191], v[212:215], v[16:19]
	v_mfma_f32_16x16x32_bf16 v[4:7], v[176:179], v[220:223], v[4:7]
	v_mfma_f32_16x16x32_bf16 v[0:3], v[188:191], v[220:223], v[0:3]
	s_setprio 0
	s_barrier
	s_add_i32 s71, s71, 2
	s_add_u32 s36, s36, 0x100
	s_addc_u32 s37, s37, 0
	s_cmp_gt_u32 s71, 29
	s_cbranch_scc0 .LBB0_620
	s_branch .Lpeel_exit_1

; #define PG8_BAR __builtin_amdgcn_s_barrier()
; template <class Epi, class Sched>
; __device__ __forceinline__ void gemm_phase(LAS unsigned char* lds, const Gemm g, const Sched& S, const Epi& E, int tid_in) {
;     ...
;         if (wr == 0) PG8_BAR;
.Lpeel_exit_1:
	s_and_b64 vcc, exec, s[20:21]
	s_cbranch_vccz .LBB0_623
	s_barrier

;     __device__ bool next(int i, Unit& u) const { if (!b.next(i >> 1, u)) return false; u.half = i & 1; u.koff = (i & 1) * kbytes; return true; }
; #define PG8_STAGE(bufoff, gbase, voff) do { _Pragma("unroll") for (int _i = 0; _i < 2; ++_i) \
;         __builtin_amdgcn_global_load_lds((const unsigned*)((const char*)(gbase) + (voff)[_i]), (LAS unsigned*)(lds + (bufoff) + ldsw + _i * 8192), 16, 0, 0); } while (0)
; #define PG8_LDA(dst, b, h) do { _Pragma("unroll") for (int m = 0; m < 4; ++m) _Pragma("unroll") for (int k = 0; k < 2; ++k) dst[m][k] = *(const LAS bf16x8*)(lds + PG8_SA(b, h) + aoff + m * 2048 + k * 1024); } while (0)
; #define PG8_LDB(dst, b, h) do { _Pragma("unroll") for (int n = 0; n < 2; ++n) _Pragma("unroll") for (int k = 0; k < 2; ++k) dst[n][k] = *(const LAS bf16x8*)(lds + PG8_SB(b, h) + boff + n * 2048 + k * 1024); } while (0)
; #define PG8_WAIT_V(n) asm volatile("s_waitcnt vmcnt(" #n ")" ::: "memory")
; #define PG8_WAIT_L(n) asm volatile("s_waitcnt lgkmcnt(" #n ")" ::: "memory")
; #define PG8_BAR __builtin_amdgcn_s_barrier()
; #define PG8_SCHED __builtin_amdgcn_sched_barrier(0)
; template <class Epi, class Sched>
; __device__ __forceinline__ void gemm_phase(LAS unsigned char* lds, const Gemm g, const Sched& S, const Epi& E, int tid_in) {
;     ...
;         const bool has_next = S.next(ui + 1, nxt);
;         const char* nA = has_next ? (const char*)g.A + (size_t)nxt.pm * tstep + nxt.koff : cA; const char* nB = has_next ? (const char*)g.Bt + (size_t)nxt.pn * tstep + nxt.koff : cB;
;         for (int t = 0; t < nt; t += 2) {
;             const bool last = (t == nt - 2);
;             const char* a1 = cA + (size_t)(t + 1) * kstep;
;             const char* a2 = last ? nA : cA + (size_t)(t + 2) * kstep; const char* b2 = last ? nB : cB + (size_t)(t + 2) * kstep;
;             const char* a3 = a2 + kstep; const char* b3 = b2 + kstep;
;             PG8_LDB(B0, 0, 0); PG8_LDB(B1, 0, 1); PG8_SCHED; PG8_LDA(At, 0, 0); PG8_STAGE(PG8_SA(1, 0), a1, voffA); PG8_STAGE(PG8_SA(1, 1), a1 + hstep, voffA);
;             PG8_WAIT_V(8); PG8_WAIT_L(0); PG8_BAR; PG8_MMA(0, 0, At, B0); PG8_MMA(0, 1, At, B1); PG8_BAR; PG8_SCHED;
;             PG8_LDA(At, 0, 1); PG8_STAGE(PG8_SB(0, 0), b2, voffB); PG8_STAGE(PG8_SB(0, 1), b2 + hstep, voffB);
;             PG8_WAIT_V(6); PG8_WAIT_L(0); PG8_BAR; PG8_MMA(1, 0, At, B0); PG8_MMA(1, 1, At, B1); PG8_BAR; PG8_SCHED;
.LBB0_762:
	s_ashr_i32 s21, s20, 31
	s_lshl_b64 s[22:23], s[20:21], 20
	s_add_u32 s22, s58, s22
	s_addc_u32 s23, s59, s23
	s_and_b64 s[24:25], s[4:5], exec
	s_cselect_b32 s21, s23, s29
	s_cselect_b32 s48, s22, s28
	s_ashr_i32 s19, s18, 31
	s_lshl_b64 s[24:25], s[18:19], 20
	s_add_u32 s24, s2, s24
	s_addc_u32 s25, s3, s25
	s_and_b64 s[34:35], s[4:5], exec
	s_cselect_b32 s19, s25, s31
	s_cselect_b32 s49, s24, s30
	s_add_u32 s51, s30, 0x100
	v_lshl_add_u64 v[144:145], s[28:29], 0, v[136:137]
	v_lshl_add_u64 v[146:147], s[28:29], 0, v[138:139]
	s_addc_u32 s68, s31, 0
	s_mov_b32 s69, -2
	s_mov_b64 s[30:31], 0
	ds_read_b128 v[154:157], v151
	ds_read_b128 v[158:161], v151 offset:1024
	ds_read_b128 v[162:165], v151 offset:2048
	ds_read_b128 v[166:169], v151 offset:3072
	ds_read_b128 v[170:173], v152
	ds_read_b128 v[174:177], v152 offset:1024
	ds_read_b128 v[178:181], v152 offset:2048
	ds_read_b128 v[182:185], v152 offset:3072
	s_add_u32 s34, s28, s30
	s_addc_u32 s35, s29, s31
	s_add_u32 s36, s34, 0x100
	s_addc_u32 s37, s35, 0
	s_add_u32 s34, s51, s30
	s_addc_u32 s35, s68, s31
	s_cmpk_eq_i32 s30, 0xf00
	s_cselect_b32 s35, s19, s35
	s_cselect_b32 s34, s49, s34
	s_cselect_b32 s37, s21, s37
	s_cselect_b32 s36, s48, s36
	v_lshl_add_u64 v[220:221], v[146:147], 0, s[30:31]
	v_lshl_add_u64 v[222:223], v[220:221], 0, s[8:9]
	s_add_i32 m0, s27, 0x8000
	ds_read_b128 v[188:191], v153
	ds_read_b128 v[192:195], v153 offset:1024
	ds_read_b128 v[196:199], v153 offset:2048
	ds_read_b128 v[200:203], v153 offset:3072
	ds_read_b128 v[204:207], v153 offset:4096
	ds_read_b128 v[208:211], v153 offset:5120
	ds_read_b128 v[212:215], v153 offset:6144
	ds_read_b128 v[216:219], v153 offset:7168
	global_load_lds_dwordx4 v[222:223], off
	v_lshl_add_u64 v[222:223], v[144:145], 0, s[30:31]
	v_lshl_add_u64 v[224:225], v[222:223], 0, s[8:9]
	s_add_i32 m0, s27, 0xa000
	v_lshl_add_u64 v[220:221], v[220:221], 0, s[14:15]
	global_load_lds_dwordx4 v[224:225], off
	s_add_i32 m0, s27, 0xc000
	s_nop 0
	global_load_lds_dwordx4 v[220:221], off
	v_lshl_add_u64 v[220:221], v[222:223], 0, s[14:15]
	s_add_i32 m0, s27, 0xe000
	s_nop 0
	global_load_lds_dwordx4 v[220:221], off
	s_waitcnt vmcnt(8)
	s_waitcnt lgkmcnt(0)
	s_barrier
	s_setprio 3
	s_waitcnt lgkmcnt(0)
	v_mfma_f32_16x16x32_bf16 v[124:127], v[154:157], v[188:191], 0
	v_mfma_f32_16x16x32_bf16 v[120:123], v[162:165], v[188:191], 0
	v_mfma_f32_16x16x32_bf16 v[108:111], v[154:157], v[196:199], 0
	v_mfma_f32_16x16x32_bf16 v[104:107], v[162:165], v[196:199], 0
	v_mfma_f32_16x16x32_bf16 v[92:95], v[154:157], v[204:207], 0
	v_mfma_f32_16x16x32_bf16 v[88:91], v[162:165], v[204:207], 0
	v_mfma_f32_16x16x32_bf16 v[76:79], v[154:157], v[212:215], 0
	v_mfma_f32_16x16x32_bf16 v[72:75], v[162:165], v[212:215], 0
	v_mfma_f32_16x16x32_bf16 v[124:127], v[158:161], v[192:195], v[124:127]
	v_mfma_f32_16x16x32_bf16 v[120:123], v[166:169], v[192:195], v[120:123]
	v_mfma_f32_16x16x32_bf16 v[108:111], v[158:161], v[200:203], v[108:111]
	v_mfma_f32_16x16x32_bf16 v[104:107], v[166:169], v[200:203], v[104:107]
	v_mfma_f32_16x16x32_bf16 v[92:95], v[158:161], v[208:211], v[92:95]
	v_mfma_f32_16x16x32_bf16 v[88:91], v[166:169], v[208:211], v[88:91]
	v_mfma_f32_16x16x32_bf16 v[76:79], v[158:161], v[216:219], v[76:79]
	v_mfma_f32_16x16x32_bf16 v[72:75], v[166:169], v[216:219], v[72:75]
	s_setprio 0
	s_setprio 3
	v_mfma_f32_16x16x32_bf16 v[116:119], v[170:173], v[188:191], 0
	v_mfma_f32_16x16x32_bf16 v[112:115], v[178:181], v[188:191], 0
	v_mfma_f32_16x16x32_bf16 v[100:103], v[170:173], v[196:199], 0
	v_mfma_f32_16x16x32_bf16 v[96:99], v[178:181], v[196:199], 0
	v_mfma_f32_16x16x32_bf16 v[84:87], v[170:173], v[204:207], 0
	v_mfma_f32_16x16x32_bf16 v[80:83], v[178:181], v[204:207], 0
	v_mfma_f32_16x16x32_bf16 v[68:71], v[170:173], v[212:215], 0
	v_mfma_f32_16x16x32_bf16 v[64:67], v[178:181], v[212:215], 0
	v_mfma_f32_16x16x32_bf16 v[116:119], v[174:177], v[192:195], v[116:119]
	v_mfma_f32_16x16x32_bf16 v[112:115], v[182:185], v[192:195], v[112:115]
	v_mfma_f32_16x16x32_bf16 v[100:103], v[174:177], v[200:203], v[100:103]
	v_mfma_f32_16x16x32_bf16 v[96:99], v[182:185], v[200:203], v[96:99]
	v_mfma_f32_16x16x32_bf16 v[84:87], v[174:177], v[208:211], v[84:87]
	v_mfma_f32_16x16x32_bf16 v[80:83], v[182:185], v[208:211], v[80:83]
	v_mfma_f32_16x16x32_bf16 v[68:71], v[174:177], v[216:219], v[68:71]
	v_mfma_f32_16x16x32_bf16 v[64:67], v[182:185], v[216:219], v[64:67]
	s_setprio 0
	s_barrier
	s_add_i32 s70, s44, s38
	v_lshl_add_u64 v[220:221], s[34:35], 0, v[132:133]
	s_mov_b32 m0, s70
	ds_read_b128 v[188:191], v153 offset:16384
	ds_read_b128 v[192:195], v153 offset:17408
	ds_read_b128 v[196:199], v153 offset:18432
	ds_read_b128 v[200:203], v153 offset:19456
	ds_read_b128 v[204:207], v153 offset:20480
	ds_read_b128 v[208:211], v153 offset:21504
	ds_read_b128 v[212:215], v153 offset:22528
	ds_read_b128 v[216:219], v153 offset:23552
	global_load_lds_dwordx4 v[220:221], off
	s_add_i32 m0, s70, 0x2000
	s_add_u32 s70, s34, 0x80000
	v_lshl_add_u64 v[222:223], s[34:35], 0, v[128:129]
	s_addc_u32 s71, s35, 0
	s_add_i32 s72, s45, s38
	global_load_lds_dwordx4 v[222:223], off
	v_lshl_add_u64 v[224:225], s[70:71], 0, v[132:133]
	s_mov_b32 m0, s72
	s_nop 0
	global_load_lds_dwordx4 v[224:225], off
	v_lshl_add_u64 v[224:225], s[70:71], 0, v[128:129]
	s_add_i32 m0, s72, 0x2000
	s_nop 0
	global_load_lds_dwordx4 v[224:225], off
	s_waitcnt vmcnt(6)
	s_waitcnt lgkmcnt(0)
	s_barrier
; #define PG8_STAGE(bufoff, gbase, voff) do { _Pragma("unroll") for (int _i = 0; _i < 2; ++_i) \
;         __builtin_amdgcn_global_load_lds((const unsigned*)((const char*)(gbase) + (voff)[_i]), (LAS unsigned*)(lds + (bufoff) + ldsw + _i * 8192), 16, 0, 0); } while (0)
; #define PG8_LDA(dst, b, h) do { _Pragma("unroll") for (int m = 0; m < 4; ++m) _Pragma("unroll") for (int k = 0; k < 2; ++k) dst[m][k] = *(const LAS bf16x8*)(lds + PG8_SA(b, h) + aoff + m * 2048 + k * 1024); } while (0)
; #define PG8_LDB(dst, b, h) do { _Pragma("unroll") for (int n = 0; n < 2; ++n) _Pragma("unroll") for (int k = 0; k < 2; ++k) dst[n][k] = *(const LAS bf16x8*)(lds + PG8_SB(b, h) + boff + n * 2048 + k * 1024); } while (0)
; #define PG8_MMA(ai, bj, At, Bt) do { __builtin_amdgcn_s_setprio(3); _Pragma("unroll") for (int m = 0; m < 4; ++m) _Pragma("unroll") for (int n = 0; n < 2; ++n) _Pragma("unroll") for (int k = 0; k < 2; ++k) \
;         acc[ai][bj][m][n] = __builtin_amdgcn_mfma_f32_16x16x32_bf16(Bt[n][k], At[m][k], acc[ai][bj][m][n], 0, 0, 0); __builtin_amdgcn_s_setprio(0); } while (0)
; #define PG8_WAIT_V(n) asm volatile("s_waitcnt vmcnt(" #n ")" ::: "memory")
; #define PG8_WAIT_L(n) asm volatile("s_waitcnt lgkmcnt(" #n ")" ::: "memory")
; #define PG8_BAR __builtin_amdgcn_s_barrier()
; #define PG8_SCHED __builtin_amdgcn_sched_barrier(0)
; template <class Epi, class Sched>
; __device__ __forceinline__ void gemm_phase(LAS unsigned char* lds, const Gemm g, const Sched& S, const Epi& E, int tid_in) {
;     ...
;             PG8_WAIT_V(6); PG8_WAIT_L(0); PG8_BAR; PG8_MMA(1, 0, At, B0); PG8_MMA(1, 1, At, B1); PG8_BAR; PG8_SCHED;
;             PG8_LDB(B0, 1, 0); PG8_LDB(B1, 1, 1); PG8_SCHED; PG8_LDA(At, 1, 0); PG8_STAGE(PG8_SA(0, 0), a2, voffA); PG8_STAGE(PG8_SA(0, 1), a2 + hstep, voffA);
;             PG8_WAIT_V(8); PG8_WAIT_L(0); PG8_BAR; PG8_MMA(0, 0, At, B0); PG8_MMA(0, 1, At, B1); PG8_BAR; PG8_SCHED;
	s_setprio 3
	s_waitcnt lgkmcnt(0)
	v_mfma_f32_16x16x32_bf16 v[60:63], v[154:157], v[188:191], 0
	v_mfma_f32_16x16x32_bf16 v[56:59], v[162:165], v[188:191], 0
	v_mfma_f32_16x16x32_bf16 v[44:47], v[154:157], v[196:199], 0
	v_mfma_f32_16x16x32_bf16 v[40:43], v[162:165], v[196:199], 0
	v_mfma_f32_16x16x32_bf16 v[28:31], v[154:157], v[204:207], 0
	v_mfma_f32_16x16x32_bf16 v[24:27], v[162:165], v[204:207], 0
	v_mfma_f32_16x16x32_bf16 v[12:15], v[154:157], v[212:215], 0
	v_mfma_f32_16x16x32_bf16 v[8:11], v[162:165], v[212:215], 0
	v_mfma_f32_16x16x32_bf16 v[60:63], v[158:161], v[192:195], v[60:63]
	v_mfma_f32_16x16x32_bf16 v[56:59], v[166:169], v[192:195], v[56:59]
	v_mfma_f32_16x16x32_bf16 v[44:47], v[158:161], v[200:203], v[44:47]
	v_mfma_f32_16x16x32_bf16 v[40:43], v[166:169], v[200:203], v[40:43]
	v_mfma_f32_16x16x32_bf16 v[28:31], v[158:161], v[208:211], v[28:31]
	v_mfma_f32_16x16x32_bf16 v[24:27], v[166:169], v[208:211], v[24:27]
	v_mfma_f32_16x16x32_bf16 v[12:15], v[158:161], v[216:219], v[12:15]
	v_mfma_f32_16x16x32_bf16 v[8:11], v[166:169], v[216:219], v[8:11]
	s_setprio 0
	s_setprio 3
	v_mfma_f32_16x16x32_bf16 v[52:55], v[170:173], v[188:191], 0
	v_mfma_f32_16x16x32_bf16 v[48:51], v[178:181], v[188:191], 0
	v_mfma_f32_16x16x32_bf16 v[36:39], v[170:173], v[196:199], 0
	v_mfma_f32_16x16x32_bf16 v[32:35], v[178:181], v[196:199], 0
	v_mfma_f32_16x16x32_bf16 v[20:23], v[170:173], v[204:207], 0
	v_mfma_f32_16x16x32_bf16 v[16:19], v[178:181], v[204:207], 0
	v_mfma_f32_16x16x32_bf16 v[4:7], v[170:173], v[212:215], 0
	v_mfma_f32_16x16x32_bf16 v[0:3], v[178:181], v[212:215], 0
	v_mfma_f32_16x16x32_bf16 v[52:55], v[174:177], v[192:195], v[52:55]
	v_mfma_f32_16x16x32_bf16 v[48:51], v[182:185], v[192:195], v[48:51]
	v_mfma_f32_16x16x32_bf16 v[36:39], v[174:177], v[200:203], v[36:39]
	v_mfma_f32_16x16x32_bf16 v[32:35], v[182:185], v[200:203], v[32:35]
	v_mfma_f32_16x16x32_bf16 v[20:23], v[174:177], v[208:211], v[20:23]
	v_mfma_f32_16x16x32_bf16 v[16:19], v[182:185], v[208:211], v[16:19]
	v_mfma_f32_16x16x32_bf16 v[4:7], v[174:177], v[216:219], v[4:7]
	v_mfma_f32_16x16x32_bf16 v[0:3], v[182:185], v[216:219], v[0:3]
	s_setprio 0
	s_barrier
	s_add_i32 s70, 0, 0x18000
	s_add_i32 s71, 0, 0x1c000
	v_add_u32_e32 v166, s70, v149
	v_add_u32_e32 v182, s71, v149
	ds_read_b128 v[154:157], v166
	ds_read_b128 v[158:161], v166 offset:1024
	ds_read_b128 v[162:165], v166 offset:2048
	ds_read_b128 v[166:169], v166 offset:3072
	ds_read_b128 v[170:173], v182
	ds_read_b128 v[174:177], v182 offset:1024
	ds_read_b128 v[178:181], v182 offset:2048
	ds_read_b128 v[182:185], v182 offset:3072
	s_mov_b32 m0, s27
	v_lshl_add_u64 v[224:225], s[36:37], 0, v[134:135]
	ds_read_b128 v[188:191], v153 offset:32768
	ds_read_b128 v[192:195], v153 offset:33792
	ds_read_b128 v[196:199], v153 offset:34816
	ds_read_b128 v[200:203], v153 offset:35840
	ds_read_b128 v[204:207], v153 offset:36864
	ds_read_b128 v[208:211], v153 offset:37888
	ds_read_b128 v[212:215], v153 offset:38912
	ds_read_b128 v[216:219], v153 offset:39936
	global_load_lds_dwordx4 v[224:225], off
	v_lshl_add_u64 v[224:225], s[36:37], 0, v[130:131]
	s_add_u32 s36, s36, 0x80000
	s_mov_b32 m0, s40
	s_addc_u32 s37, s37, 0
	global_load_lds_dwordx4 v[224:225], off
	v_lshl_add_u64 v[224:225], s[36:37], 0, v[134:135]
	s_mov_b32 m0, s41
	s_nop 0
	global_load_lds_dwordx4 v[224:225], off
	v_lshl_add_u64 v[224:225], s[36:37], 0, v[130:131]
	s_mov_b32 m0, s42
	s_nop 0
	global_load_lds_dwordx4 v[224:225], off
	s_waitcnt vmcnt(8)
	s_waitcnt lgkmcnt(0)
	s_barrier
; #define PG8_STAGE(bufoff, gbase, voff) do { _Pragma("unroll") for (int _i = 0; _i < 2; ++_i) \
;         __builtin_amdgcn_global_load_lds((const unsigned*)((const char*)(gbase) + (voff)[_i]), (LAS unsigned*)(lds + (bufoff) + ldsw + _i * 8192), 16, 0, 0); } while (0)
; #define PG8_LDA(dst, b, h) do { _Pragma("unroll") for (int m = 0; m < 4; ++m) _Pragma("unroll") for (int k = 0; k < 2; ++k) dst[m][k] = *(const LAS bf16x8*)(lds + PG8_SA(b, h) + aoff + m * 2048 + k * 1024); } while (0)
; #define PG8_MMA(ai, bj, At, Bt) do { __builtin_amdgcn_s_setprio(3); _Pragma("unroll") for (int m = 0; m < 4; ++m) _Pragma("unroll") for (int n = 0; n < 2; ++n) _Pragma("unroll") for (int k = 0; k < 2; ++k) \
;         acc[ai][bj][m][n] = __builtin_amdgcn_mfma_f32_16x16x32_bf16(Bt[n][k], At[m][k], acc[ai][bj][m][n], 0, 0, 0); __builtin_amdgcn_s_setprio(0); } while (0)
; #define PG8_WAIT_V(n) asm volatile("s_waitcnt vmcnt(" #n ")" ::: "memory")
; #define PG8_WAIT_L(n) asm volatile("s_waitcnt lgkmcnt(" #n ")" ::: "memory")
; #define PG8_BAR __builtin_amdgcn_s_barrier()
; #define PG8_SCHED __builtin_amdgcn_sched_barrier(0)
; template <class Epi, class Sched>
; __device__ __forceinline__ void gemm_phase(LAS unsigned char* lds, const Gemm g, const Sched& S, const Epi& E, int tid_in) {
;     ...
;             PG8_WAIT_V(8); PG8_WAIT_L(0); PG8_BAR; PG8_MMA(0, 0, At, B0); PG8_MMA(0, 1, At, B1); PG8_BAR; PG8_SCHED;
;             PG8_LDA(At, 1, 1); PG8_STAGE(PG8_SB(1, 0), b3, voffB); PG8_STAGE(PG8_SB(1, 1), b3 + hstep, voffB);
;             PG8_WAIT_V(6); PG8_WAIT_L(0); PG8_BAR; PG8_MMA(1, 0, At, B0); PG8_MMA(1, 1, At, B1); PG8_BAR; PG8_SCHED;
;         }
	s_setprio 3
	s_waitcnt lgkmcnt(0)
	v_mfma_f32_16x16x32_bf16 v[124:127], v[154:157], v[188:191], v[124:127]
	v_mfma_f32_16x16x32_bf16 v[120:123], v[162:165], v[188:191], v[120:123]
	v_mfma_f32_16x16x32_bf16 v[108:111], v[154:157], v[196:199], v[108:111]
	v_mfma_f32_16x16x32_bf16 v[104:107], v[162:165], v[196:199], v[104:107]
	v_mfma_f32_16x16x32_bf16 v[92:95], v[154:157], v[204:207], v[92:95]
	v_mfma_f32_16x16x32_bf16 v[88:91], v[162:165], v[204:207], v[88:91]
	v_mfma_f32_16x16x32_bf16 v[76:79], v[154:157], v[212:215], v[76:79]
	v_mfma_f32_16x16x32_bf16 v[72:75], v[162:165], v[212:215], v[72:75]
	v_mfma_f32_16x16x32_bf16 v[124:127], v[158:161], v[192:195], v[124:127]
	v_mfma_f32_16x16x32_bf16 v[120:123], v[166:169], v[192:195], v[120:123]
	v_mfma_f32_16x16x32_bf16 v[108:111], v[158:161], v[200:203], v[108:111]
	v_mfma_f32_16x16x32_bf16 v[104:107], v[166:169], v[200:203], v[104:107]
	v_mfma_f32_16x16x32_bf16 v[92:95], v[158:161], v[208:211], v[92:95]
	v_mfma_f32_16x16x32_bf16 v[88:91], v[166:169], v[208:211], v[88:91]
	v_mfma_f32_16x16x32_bf16 v[76:79], v[158:161], v[216:219], v[76:79]
	v_mfma_f32_16x16x32_bf16 v[72:75], v[166:169], v[216:219], v[72:75]
	s_setprio 0
	s_setprio 3
	v_mfma_f32_16x16x32_bf16 v[116:119], v[170:173], v[188:191], v[116:119]
	v_mfma_f32_16x16x32_bf16 v[112:115], v[178:181], v[188:191], v[112:115]
	v_mfma_f32_16x16x32_bf16 v[100:103], v[170:173], v[196:199], v[100:103]
	v_mfma_f32_16x16x32_bf16 v[96:99], v[178:181], v[196:199], v[96:99]
	v_mfma_f32_16x16x32_bf16 v[84:87], v[170:173], v[204:207], v[84:87]
	v_mfma_f32_16x16x32_bf16 v[80:83], v[178:181], v[204:207], v[80:83]
	v_mfma_f32_16x16x32_bf16 v[68:71], v[170:173], v[212:215], v[68:71]
	v_mfma_f32_16x16x32_bf16 v[64:67], v[178:181], v[212:215], v[64:67]
	v_mfma_f32_16x16x32_bf16 v[116:119], v[174:177], v[192:195], v[116:119]
	v_mfma_f32_16x16x32_bf16 v[112:115], v[182:185], v[192:195], v[112:115]
	v_mfma_f32_16x16x32_bf16 v[100:103], v[174:177], v[200:203], v[100:103]
	v_mfma_f32_16x16x32_bf16 v[96:99], v[182:185], v[200:203], v[96:99]
	v_mfma_f32_16x16x32_bf16 v[84:87], v[174:177], v[208:211], v[84:87]
	v_mfma_f32_16x16x32_bf16 v[80:83], v[182:185], v[208:211], v[80:83]
	v_mfma_f32_16x16x32_bf16 v[68:71], v[174:177], v[216:219], v[68:71]
	v_mfma_f32_16x16x32_bf16 v[64:67], v[182:185], v[216:219], v[64:67]
	s_setprio 0
	s_barrier
	s_add_i32 s36, s70, s38
	v_lshl_add_u64 v[220:221], v[220:221], 0, s[8:9]
	s_mov_b32 m0, s36
	ds_read_b128 v[188:191], v153 offset:49152
	ds_read_b128 v[192:195], v153 offset:50176
	ds_read_b128 v[196:199], v153 offset:51200
	ds_read_b128 v[200:203], v153 offset:52224
	ds_read_b128 v[204:207], v153 offset:53248
	ds_read_b128 v[208:211], v153 offset:54272
	ds_read_b128 v[212:215], v153 offset:55296
	ds_read_b128 v[216:219], v153 offset:56320
	global_load_lds_dwordx4 v[220:221], off
	s_add_i32 m0, s36, 0x2000
	s_add_u32 s34, s34, 0x80080
	v_lshl_add_u64 v[220:221], v[222:223], 0, s[8:9]
	s_addc_u32 s35, s35, 0
	s_add_i32 s36, s71, s38
	global_load_lds_dwordx4 v[220:221], off
	v_lshl_add_u64 v[220:221], s[34:35], 0, v[132:133]
	s_mov_b32 m0, s36
	s_nop 0
	global_load_lds_dwordx4 v[220:221], off
	v_lshl_add_u64 v[220:221], s[34:35], 0, v[128:129]
	s_add_i32 m0, s36, 0x2000
	s_nop 0
	global_load_lds_dwordx4 v[220:221], off
	s_waitcnt vmcnt(6)
	s_waitcnt lgkmcnt(0)
	s_barrier
	s_setprio 3
	s_waitcnt lgkmcnt(0)
	v_mfma_f32_16x16x32_bf16 v[60:63], v[154:157], v[188:191], v[60:63]
	v_mfma_f32_16x16x32_bf16 v[56:59], v[162:165], v[188:191], v[56:59]
	v_mfma_f32_16x16x32_bf16 v[44:47], v[154:157], v[196:199], v[44:47]
	v_mfma_f32_16x16x32_bf16 v[40:43], v[162:165], v[196:199], v[40:43]
	v_mfma_f32_16x16x32_bf16 v[28:31], v[154:157], v[204:207], v[28:31]
	v_mfma_f32_16x16x32_bf16 v[24:27], v[162:165], v[204:207], v[24:27]
	v_mfma_f32_16x16x32_bf16 v[12:15], v[154:157], v[212:215], v[12:15]
	v_mfma_f32_16x16x32_bf16 v[8:11], v[162:165], v[212:215], v[8:11]
	v_mfma_f32_16x16x32_bf16 v[60:63], v[158:161], v[192:195], v[60:63]
	v_mfma_f32_16x16x32_bf16 v[56:59], v[166:169], v[192:195], v[56:59]
	v_mfma_f32_16x16x32_bf16 v[44:47], v[158:161], v[200:203], v[44:47]
	v_mfma_f32_16x16x32_bf16 v[40:43], v[166:169], v[200:203], v[40:43]
	v_mfma_f32_16x16x32_bf16 v[28:31], v[158:161], v[208:211], v[28:31]
	v_mfma_f32_16x16x32_bf16 v[24:27], v[166:169], v[208:211], v[24:27]
	v_mfma_f32_16x16x32_bf16 v[12:15], v[158:161], v[216:219], v[12:15]
	v_mfma_f32_16x16x32_bf16 v[8:11], v[166:169], v[216:219], v[8:11]
	s_setprio 0
	s_setprio 3
	v_mfma_f32_16x16x32_bf16 v[52:55], v[170:173], v[188:191], v[52:55]
	v_mfma_f32_16x16x32_bf16 v[48:51], v[178:181], v[188:191], v[48:51]
	v_mfma_f32_16x16x32_bf16 v[36:39], v[170:173], v[196:199], v[36:39]
	v_mfma_f32_16x16x32_bf16 v[32:35], v[178:181], v[196:199], v[32:35]
	v_mfma_f32_16x16x32_bf16 v[20:23], v[170:173], v[204:207], v[20:23]
	v_mfma_f32_16x16x32_bf16 v[16:19], v[178:181], v[204:207], v[16:19]
	v_mfma_f32_16x16x32_bf16 v[4:7], v[170:173], v[212:215], v[4:7]
	v_mfma_f32_16x16x32_bf16 v[0:3], v[178:181], v[212:215], v[0:3]
	v_mfma_f32_16x16x32_bf16 v[52:55], v[174:177], v[192:195], v[52:55]
	v_mfma_f32_16x16x32_bf16 v[48:51], v[182:185], v[192:195], v[48:51]
	v_mfma_f32_16x16x32_bf16 v[36:39], v[174:177], v[200:203], v[36:39]
	v_mfma_f32_16x16x32_bf16 v[32:35], v[182:185], v[200:203], v[32:35]
	v_mfma_f32_16x16x32_bf16 v[20:23], v[174:177], v[208:211], v[20:23]
	v_mfma_f32_16x16x32_bf16 v[16:19], v[182:185], v[208:211], v[16:19]
	v_mfma_f32_16x16x32_bf16 v[4:7], v[174:177], v[216:219], v[4:7]
	v_mfma_f32_16x16x32_bf16 v[0:3], v[182:185], v[216:219], v[0:3]
	s_setprio 0
	s_barrier
	s_add_i32 s69, s69, 2
	s_add_u32 s30, s30, 0x100
	s_addc_u32 s31, s31, 0
	s_cmp_gt_u32 s69, 29
	s_cbranch_scc0 .LBB0_763
	s_branch .Lpeel_exit_2

; #define PG8_BAR __builtin_amdgcn_s_barrier()
; template <class Epi, class Sched>
; __device__ __forceinline__ void gemm_phase(LAS unsigned char* lds, const Gemm g, const Sched& S, const Epi& E, int tid_in) {
;     ...
;         if (wr == 0) PG8_BAR;
.Lpeel_exit_2:
	s_and_b64 vcc, exec, s[16:17]
	s_cbranch_vccz .LBB0_766
	s_barrier

;     __device__ bool next(int i, Unit& u) const { if (!b.next(i >> 1, u)) return false; u.half = i & 1; u.koff = (i & 1) * kbytes; return true; }
; #define PG8_STAGE(bufoff, gbase, voff) do { _Pragma("unroll") for (int _i = 0; _i < 2; ++_i) \
;         __builtin_amdgcn_global_load_lds((const unsigned*)((const char*)(gbase) + (voff)[_i]), (LAS unsigned*)(lds + (bufoff) + ldsw + _i * 8192), 16, 0, 0); } while (0)
; #define PG8_LDA(dst, b, h) do { _Pragma("unroll") for (int m = 0; m < 4; ++m) _Pragma("unroll") for (int k = 0; k < 2; ++k) dst[m][k] = *(const LAS bf16x8*)(lds + PG8_SA(b, h) + aoff + m * 2048 + k * 1024); } while (0)
; #define PG8_LDB(dst, b, h) do { _Pragma("unroll") for (int n = 0; n < 2; ++n) _Pragma("unroll") for (int k = 0; k < 2; ++k) dst[n][k] = *(const LAS bf16x8*)(lds + PG8_SB(b, h) + boff + n * 2048 + k * 1024); } while (0)
; #define PG8_WAIT_V(n) asm volatile("s_waitcnt vmcnt(" #n ")" ::: "memory")
; #define PG8_WAIT_L(n) asm volatile("s_waitcnt lgkmcnt(" #n ")" ::: "memory")
; #define PG8_BAR __builtin_amdgcn_s_barrier()
; #define PG8_SCHED __builtin_amdgcn_sched_barrier(0)
; template <class Epi, class Sched>
; __device__ __forceinline__ void gemm_phase(LAS unsigned char* lds, const Gemm g, const Sched& S, const Epi& E, int tid_in) {
;     ...
;         const bool has_next = S.next(ui + 1, nxt);
;         const char* nA = has_next ? (const char*)g.A + (size_t)nxt.pm * tstep + nxt.koff : cA; const char* nB = has_next ? (const char*)g.Bt + (size_t)nxt.pn * tstep + nxt.koff : cB;
;         for (int t = 0; t < nt; t += 2) {
;             const bool last = (t == nt - 2);
;             const char* a1 = cA + (size_t)(t + 1) * kstep;
;             const char* a2 = last ? nA : cA + (size_t)(t + 2) * kstep; const char* b2 = last ? nB : cB + (size_t)(t + 2) * kstep;
;             const char* a3 = a2 + kstep; const char* b3 = b2 + kstep;
;             PG8_LDB(B0, 0, 0); PG8_LDB(B1, 0, 1); PG8_SCHED; PG8_LDA(At, 0, 0); PG8_STAGE(PG8_SA(1, 0), a1, voffA); PG8_STAGE(PG8_SA(1, 1), a1 + hstep, voffA);
;             PG8_WAIT_V(8); PG8_WAIT_L(0); PG8_BAR; PG8_MMA(0, 0, At, B0); PG8_MMA(0, 1, At, B1); PG8_BAR; PG8_SCHED;
;             PG8_LDA(At, 0, 1); PG8_STAGE(PG8_SB(0, 0), b2, voffB); PG8_STAGE(PG8_SB(0, 1), b2 + hstep, voffB);
;             PG8_WAIT_V(6); PG8_WAIT_L(0); PG8_BAR; PG8_MMA(1, 0, At, B0); PG8_MMA(1, 1, At, B1); PG8_BAR; PG8_SCHED;
.LBB0_841:
	s_add_u32 s46, s28, 0x100
	s_addc_u32 s47, s29, 0
	v_lshl_add_u64 v[144:145], s[26:27], 0, v[136:137]
	v_lshl_add_u64 v[146:147], s[26:27], 0, v[138:139]
	s_mov_b32 s48, -2
	s_mov_b64 s[28:29], 0
	s_waitcnt lgkmcnt(0)
	ds_read_b128 v[156:159], v151
	ds_read_b128 v[160:163], v151 offset:1024
	ds_read_b128 v[164:167], v151 offset:2048
	ds_read_b128 v[168:171], v151 offset:3072
	ds_read_b128 v[172:175], v152
	ds_read_b128 v[176:179], v152 offset:1024
	ds_read_b128 v[180:183], v152 offset:2048
	ds_read_b128 v[188:191], v152 offset:3072
	s_add_u32 s30, s26, s28
	s_addc_u32 s31, s27, s29
	s_add_u32 s34, s30, 0x100
	s_addc_u32 s35, s31, 0
	s_add_u32 s30, s46, s28
	s_addc_u32 s31, s47, s29
	s_cmpk_eq_i32 s28, 0x2b00
	s_cselect_b32 s31, s25, s31
	s_cselect_b32 s30, s24, s30
	s_cselect_b32 s35, s7, s35
	s_cselect_b32 s34, s6, s34
	v_lshl_add_u64 v[184:185], v[144:145], 0, s[28:29]
	v_lshl_add_u64 v[224:225], v[184:185], 0, s[18:19]
	s_add_i32 m0, s3, 0x8000
	ds_read_b128 v[192:195], v153
	ds_read_b128 v[196:199], v153 offset:1024
	ds_read_b128 v[200:203], v153 offset:2048
	ds_read_b128 v[204:207], v153 offset:3072
	ds_read_b128 v[208:211], v153 offset:4096
	ds_read_b128 v[212:215], v153 offset:5120
	ds_read_b128 v[216:219], v153 offset:6144
	ds_read_b128 v[220:223], v153 offset:7168
	global_load_lds_dwordx4 v[224:225], off
	v_lshl_add_u64 v[224:225], v[146:147], 0, s[28:29]
	v_lshl_add_u64 v[226:227], v[224:225], 0, s[18:19]
	s_add_i32 m0, s3, 0xa000
	v_lshl_add_u64 v[184:185], v[184:185], 0, s[20:21]
	global_load_lds_dwordx4 v[226:227], off
	s_add_i32 m0, s3, 0xc000
	s_nop 0
	global_load_lds_dwordx4 v[184:185], off
	v_lshl_add_u64 v[184:185], v[224:225], 0, s[20:21]
	s_add_i32 m0, s3, 0xe000
	s_nop 0
	global_load_lds_dwordx4 v[184:185], off
	s_waitcnt vmcnt(8)
	s_waitcnt lgkmcnt(0)
	s_barrier
	s_setprio 3
	s_waitcnt lgkmcnt(0)
	v_mfma_f32_16x16x32_bf16 v[124:127], v[156:159], v[192:195], 0
	v_mfma_f32_16x16x32_bf16 v[120:123], v[164:167], v[192:195], 0
	v_mfma_f32_16x16x32_bf16 v[108:111], v[156:159], v[200:203], 0
	v_mfma_f32_16x16x32_bf16 v[104:107], v[164:167], v[200:203], 0
	v_mfma_f32_16x16x32_bf16 v[92:95], v[156:159], v[208:211], 0
	v_mfma_f32_16x16x32_bf16 v[88:91], v[164:167], v[208:211], 0
	v_mfma_f32_16x16x32_bf16 v[76:79], v[156:159], v[216:219], 0
	v_mfma_f32_16x16x32_bf16 v[72:75], v[164:167], v[216:219], 0
	v_mfma_f32_16x16x32_bf16 v[124:127], v[160:163], v[196:199], v[124:127]
	v_mfma_f32_16x16x32_bf16 v[120:123], v[168:171], v[196:199], v[120:123]
	v_mfma_f32_16x16x32_bf16 v[108:111], v[160:163], v[204:207], v[108:111]
	v_mfma_f32_16x16x32_bf16 v[104:107], v[168:171], v[204:207], v[104:107]
	v_mfma_f32_16x16x32_bf16 v[92:95], v[160:163], v[212:215], v[92:95]
	v_mfma_f32_16x16x32_bf16 v[88:91], v[168:171], v[212:215], v[88:91]
	v_mfma_f32_16x16x32_bf16 v[76:79], v[160:163], v[220:223], v[76:79]
	v_mfma_f32_16x16x32_bf16 v[72:75], v[168:171], v[220:223], v[72:75]
	s_setprio 0
	s_setprio 3
	v_mfma_f32_16x16x32_bf16 v[116:119], v[172:175], v[192:195], 0
	v_mfma_f32_16x16x32_bf16 v[112:115], v[180:183], v[192:195], 0
	v_mfma_f32_16x16x32_bf16 v[100:103], v[172:175], v[200:203], 0
	v_mfma_f32_16x16x32_bf16 v[96:99], v[180:183], v[200:203], 0
	v_mfma_f32_16x16x32_bf16 v[84:87], v[172:175], v[208:211], 0
	v_mfma_f32_16x16x32_bf16 v[80:83], v[180:183], v[208:211], 0
	v_mfma_f32_16x16x32_bf16 v[68:71], v[172:175], v[216:219], 0
	v_mfma_f32_16x16x32_bf16 v[64:67], v[180:183], v[216:219], 0
	v_mfma_f32_16x16x32_bf16 v[116:119], v[176:179], v[196:199], v[116:119]
	v_mfma_f32_16x16x32_bf16 v[112:115], v[188:191], v[196:199], v[112:115]
	v_mfma_f32_16x16x32_bf16 v[100:103], v[176:179], v[204:207], v[100:103]
	v_mfma_f32_16x16x32_bf16 v[96:99], v[188:191], v[204:207], v[96:99]
	v_mfma_f32_16x16x32_bf16 v[84:87], v[176:179], v[212:215], v[84:87]
	v_mfma_f32_16x16x32_bf16 v[80:83], v[188:191], v[212:215], v[80:83]
	v_mfma_f32_16x16x32_bf16 v[68:71], v[176:179], v[220:223], v[68:71]
	v_mfma_f32_16x16x32_bf16 v[64:67], v[188:191], v[220:223], v[64:67]
	s_setprio 0
	s_barrier
	s_add_i32 s49, s40, s2
	v_lshl_add_u64 v[184:185], s[30:31], 0, v[130:131]
	s_mov_b32 m0, s49
	ds_read_b128 v[192:195], v153 offset:16384
	ds_read_b128 v[196:199], v153 offset:17408
	ds_read_b128 v[200:203], v153 offset:18432
	ds_read_b128 v[204:207], v153 offset:19456
	ds_read_b128 v[208:211], v153 offset:20480
	ds_read_b128 v[212:215], v153 offset:21504
	ds_read_b128 v[216:219], v153 offset:22528
	ds_read_b128 v[220:223], v153 offset:23552
	global_load_lds_dwordx4 v[184:185], off
	s_add_i32 m0, s49, 0x2000
	s_add_u32 s68, s30, 0x160000
	v_lshl_add_u64 v[224:225], s[30:31], 0, v[134:135]
	s_addc_u32 s69, s31, 0
	s_add_i32 s49, s41, s2
	global_load_lds_dwordx4 v[224:225], off
	v_lshl_add_u64 v[226:227], s[68:69], 0, v[130:131]
	s_mov_b32 m0, s49
	s_nop 0
	global_load_lds_dwordx4 v[226:227], off
	v_lshl_add_u64 v[226:227], s[68:69], 0, v[134:135]
	s_add_i32 m0, s49, 0x2000
	s_nop 0
	global_load_lds_dwordx4 v[226:227], off
	s_waitcnt vmcnt(6)
	s_waitcnt lgkmcnt(0)
	s_barrier
; #define PG8_STAGE(bufoff, gbase, voff) do { _Pragma("unroll") for (int _i = 0; _i < 2; ++_i) \
;         __builtin_amdgcn_global_load_lds((const unsigned*)((const char*)(gbase) + (voff)[_i]), (LAS unsigned*)(lds + (bufoff) + ldsw + _i * 8192), 16, 0, 0); } while (0)
; #define PG8_LDA(dst, b, h) do { _Pragma("unroll") for (int m = 0; m < 4; ++m) _Pragma("unroll") for (int k = 0; k < 2; ++k) dst[m][k] = *(const LAS bf16x8*)(lds + PG8_SA(b, h) + aoff + m * 2048 + k * 1024); } while (0)
; #define PG8_LDB(dst, b, h) do { _Pragma("unroll") for (int n = 0; n < 2; ++n) _Pragma("unroll") for (int k = 0; k < 2; ++k) dst[n][k] = *(const LAS bf16x8*)(lds + PG8_SB(b, h) + boff + n * 2048 + k * 1024); } while (0)
; #define PG8_MMA(ai, bj, At, Bt) do { __builtin_amdgcn_s_setprio(3); _Pragma("unroll") for (int m = 0; m < 4; ++m) _Pragma("unroll") for (int n = 0; n < 2; ++n) _Pragma("unroll") for (int k = 0; k < 2; ++k) \
;         acc[ai][bj][m][n] = __builtin_amdgcn_mfma_f32_16x16x32_bf16(Bt[n][k], At[m][k], acc[ai][bj][m][n], 0, 0, 0); __builtin_amdgcn_s_setprio(0); } while (0)
; #define PG8_WAIT_V(n) asm volatile("s_waitcnt vmcnt(" #n ")" ::: "memory")
; #define PG8_WAIT_L(n) asm volatile("s_waitcnt lgkmcnt(" #n ")" ::: "memory")
; #define PG8_BAR __builtin_amdgcn_s_barrier()
; #define PG8_SCHED __builtin_amdgcn_sched_barrier(0)
; template <class Epi, class Sched>
; __device__ __forceinline__ void gemm_phase(LAS unsigned char* lds, const Gemm g, const Sched& S, const Epi& E, int tid_in) {
;     ...
;             PG8_WAIT_V(6); PG8_WAIT_L(0); PG8_BAR; PG8_MMA(1, 0, At, B0); PG8_MMA(1, 1, At, B1); PG8_BAR; PG8_SCHED;
;             PG8_LDB(B0, 1, 0); PG8_LDB(B1, 1, 1); PG8_SCHED; PG8_LDA(At, 1, 0); PG8_STAGE(PG8_SA(0, 0), a2, voffA); PG8_STAGE(PG8_SA(0, 1), a2 + hstep, voffA);
;             PG8_WAIT_V(8); PG8_WAIT_L(0); PG8_BAR; PG8_MMA(0, 0, At, B0); PG8_MMA(0, 1, At, B1); PG8_BAR; PG8_SCHED;
	s_setprio 3
	s_waitcnt lgkmcnt(0)
	v_mfma_f32_16x16x32_bf16 v[60:63], v[156:159], v[192:195], 0
	v_mfma_f32_16x16x32_bf16 v[56:59], v[164:167], v[192:195], 0
	v_mfma_f32_16x16x32_bf16 v[44:47], v[156:159], v[200:203], 0
	v_mfma_f32_16x16x32_bf16 v[40:43], v[164:167], v[200:203], 0
	v_mfma_f32_16x16x32_bf16 v[28:31], v[156:159], v[208:211], 0
	v_mfma_f32_16x16x32_bf16 v[24:27], v[164:167], v[208:211], 0
	v_mfma_f32_16x16x32_bf16 v[12:15], v[156:159], v[216:219], 0
	v_mfma_f32_16x16x32_bf16 v[8:11], v[164:167], v[216:219], 0
	v_mfma_f32_16x16x32_bf16 v[60:63], v[160:163], v[196:199], v[60:63]
	v_mfma_f32_16x16x32_bf16 v[56:59], v[168:171], v[196:199], v[56:59]
	v_mfma_f32_16x16x32_bf16 v[44:47], v[160:163], v[204:207], v[44:47]
	v_mfma_f32_16x16x32_bf16 v[40:43], v[168:171], v[204:207], v[40:43]
	v_mfma_f32_16x16x32_bf16 v[28:31], v[160:163], v[212:215], v[28:31]
	v_mfma_f32_16x16x32_bf16 v[24:27], v[168:171], v[212:215], v[24:27]
	v_mfma_f32_16x16x32_bf16 v[12:15], v[160:163], v[220:223], v[12:15]
	v_mfma_f32_16x16x32_bf16 v[8:11], v[168:171], v[220:223], v[8:11]
	s_setprio 0
	s_setprio 3
	v_mfma_f32_16x16x32_bf16 v[52:55], v[172:175], v[192:195], 0
	v_mfma_f32_16x16x32_bf16 v[48:51], v[180:183], v[192:195], 0
	v_mfma_f32_16x16x32_bf16 v[36:39], v[172:175], v[200:203], 0
	v_mfma_f32_16x16x32_bf16 v[32:35], v[180:183], v[200:203], 0
	v_mfma_f32_16x16x32_bf16 v[20:23], v[172:175], v[208:211], 0
	v_mfma_f32_16x16x32_bf16 v[16:19], v[180:183], v[208:211], 0
	v_mfma_f32_16x16x32_bf16 v[4:7], v[172:175], v[216:219], 0
	v_mfma_f32_16x16x32_bf16 v[0:3], v[180:183], v[216:219], 0
	v_mfma_f32_16x16x32_bf16 v[52:55], v[176:179], v[196:199], v[52:55]
	v_mfma_f32_16x16x32_bf16 v[48:51], v[188:191], v[196:199], v[48:51]
	v_mfma_f32_16x16x32_bf16 v[36:39], v[176:179], v[204:207], v[36:39]
	v_mfma_f32_16x16x32_bf16 v[32:35], v[188:191], v[204:207], v[32:35]
	v_mfma_f32_16x16x32_bf16 v[20:23], v[176:179], v[212:215], v[20:23]
	v_mfma_f32_16x16x32_bf16 v[16:19], v[188:191], v[212:215], v[16:19]
	v_mfma_f32_16x16x32_bf16 v[4:7], v[176:179], v[220:223], v[4:7]
	v_mfma_f32_16x16x32_bf16 v[0:3], v[188:191], v[220:223], v[0:3]
	s_setprio 0
	s_barrier
	s_add_i32 s49, 0, 0x18000
	v_add_u32_e32 v155, s49, v149
	s_add_i32 s51, 0, 0x1c000
	ds_read_b128 v[156:159], v155
	ds_read_b128 v[160:163], v155 offset:1024
	ds_read_b128 v[164:167], v155 offset:2048
	ds_read_b128 v[168:171], v155 offset:3072
	v_add_u32_e32 v155, s51, v149
	ds_read_b128 v[172:175], v155
	ds_read_b128 v[176:179], v155 offset:1024
	ds_read_b128 v[180:183], v155 offset:2048
	ds_read_b128 v[188:191], v155 offset:3072
	s_mov_b32 m0, s3
	v_lshl_add_u64 v[226:227], s[34:35], 0, v[128:129]
	ds_read_b128 v[192:195], v153 offset:32768
	ds_read_b128 v[196:199], v153 offset:33792
	ds_read_b128 v[200:203], v153 offset:34816
	ds_read_b128 v[204:207], v153 offset:35840
	ds_read_b128 v[208:211], v153 offset:36864
	ds_read_b128 v[212:215], v153 offset:37888
	ds_read_b128 v[216:219], v153 offset:38912
	ds_read_b128 v[220:223], v153 offset:39936
	global_load_lds_dwordx4 v[226:227], off
	v_lshl_add_u64 v[226:227], s[34:35], 0, v[132:133]
	s_add_u32 s34, s34, 0x160000
	s_mov_b32 m0, s36
	s_addc_u32 s35, s35, 0
	global_load_lds_dwordx4 v[226:227], off
	v_lshl_add_u64 v[226:227], s[34:35], 0, v[128:129]
	s_mov_b32 m0, s37
	s_nop 0
	global_load_lds_dwordx4 v[226:227], off
	v_lshl_add_u64 v[226:227], s[34:35], 0, v[132:133]
	s_mov_b32 m0, s38
	s_nop 0
	global_load_lds_dwordx4 v[226:227], off
	s_waitcnt vmcnt(8)
	s_waitcnt lgkmcnt(0)
	s_barrier
; #define PG8_STAGE(bufoff, gbase, voff) do { _Pragma("unroll") for (int _i = 0; _i < 2; ++_i) \
;         __builtin_amdgcn_global_load_lds((const unsigned*)((const char*)(gbase) + (voff)[_i]), (LAS unsigned*)(lds + (bufoff) + ldsw + _i * 8192), 16, 0, 0); } while (0)
; #define PG8_LDA(dst, b, h) do { _Pragma("unroll") for (int m = 0; m < 4; ++m) _Pragma("unroll") for (int k = 0; k < 2; ++k) dst[m][k] = *(const LAS bf16x8*)(lds + PG8_SA(b, h) + aoff + m * 2048 + k * 1024); } while (0)
; #define PG8_MMA(ai, bj, At, Bt) do { __builtin_amdgcn_s_setprio(3); _Pragma("unroll") for (int m = 0; m < 4; ++m) _Pragma("unroll") for (int n = 0; n < 2; ++n) _Pragma("unroll") for (int k = 0; k < 2; ++k) \
;         acc[ai][bj][m][n] = __builtin_amdgcn_mfma_f32_16x16x32_bf16(Bt[n][k], At[m][k], acc[ai][bj][m][n], 0, 0, 0); __builtin_amdgcn_s_setprio(0); } while (0)
; #define PG8_WAIT_V(n) asm volatile("s_waitcnt vmcnt(" #n ")" ::: "memory")
; #define PG8_WAIT_L(n) asm volatile("s_waitcnt lgkmcnt(" #n ")" ::: "memory")
; #define PG8_BAR __builtin_amdgcn_s_barrier()
; #define PG8_SCHED __builtin_amdgcn_sched_barrier(0)
; template <class Epi, class Sched>
; __device__ __forceinline__ void gemm_phase(LAS unsigned char* lds, const Gemm g, const Sched& S, const Epi& E, int tid_in) {
;     ...
;             PG8_WAIT_V(8); PG8_WAIT_L(0); PG8_BAR; PG8_MMA(0, 0, At, B0); PG8_MMA(0, 1, At, B1); PG8_BAR; PG8_SCHED;
;             PG8_LDA(At, 1, 1); PG8_STAGE(PG8_SB(1, 0), b3, voffB); PG8_STAGE(PG8_SB(1, 1), b3 + hstep, voffB);
;             PG8_WAIT_V(6); PG8_WAIT_L(0); PG8_BAR; PG8_MMA(1, 0, At, B0); PG8_MMA(1, 1, At, B1); PG8_BAR; PG8_SCHED;
;         }
	s_setprio 3
	s_waitcnt lgkmcnt(0)
	v_mfma_f32_16x16x32_bf16 v[124:127], v[156:159], v[192:195], v[124:127]
	v_mfma_f32_16x16x32_bf16 v[120:123], v[164:167], v[192:195], v[120:123]
	v_mfma_f32_16x16x32_bf16 v[108:111], v[156:159], v[200:203], v[108:111]
	v_mfma_f32_16x16x32_bf16 v[104:107], v[164:167], v[200:203], v[104:107]
	v_mfma_f32_16x16x32_bf16 v[92:95], v[156:159], v[208:211], v[92:95]
	v_mfma_f32_16x16x32_bf16 v[88:91], v[164:167], v[208:211], v[88:91]
	v_mfma_f32_16x16x32_bf16 v[76:79], v[156:159], v[216:219], v[76:79]
	v_mfma_f32_16x16x32_bf16 v[72:75], v[164:167], v[216:219], v[72:75]
	v_mfma_f32_16x16x32_bf16 v[124:127], v[160:163], v[196:199], v[124:127]
	v_mfma_f32_16x16x32_bf16 v[120:123], v[168:171], v[196:199], v[120:123]
	v_mfma_f32_16x16x32_bf16 v[108:111], v[160:163], v[204:207], v[108:111]
	v_mfma_f32_16x16x32_bf16 v[104:107], v[168:171], v[204:207], v[104:107]
	v_mfma_f32_16x16x32_bf16 v[92:95], v[160:163], v[212:215], v[92:95]
	v_mfma_f32_16x16x32_bf16 v[88:91], v[168:171], v[212:215], v[88:91]
	v_mfma_f32_16x16x32_bf16 v[76:79], v[160:163], v[220:223], v[76:79]
	v_mfma_f32_16x16x32_bf16 v[72:75], v[168:171], v[220:223], v[72:75]
	s_setprio 0
	s_setprio 3
	v_mfma_f32_16x16x32_bf16 v[116:119], v[172:175], v[192:195], v[116:119]
	v_mfma_f32_16x16x32_bf16 v[112:115], v[180:183], v[192:195], v[112:115]
	v_mfma_f32_16x16x32_bf16 v[100:103], v[172:175], v[200:203], v[100:103]
	v_mfma_f32_16x16x32_bf16 v[96:99], v[180:183], v[200:203], v[96:99]
	v_mfma_f32_16x16x32_bf16 v[84:87], v[172:175], v[208:211], v[84:87]
	v_mfma_f32_16x16x32_bf16 v[80:83], v[180:183], v[208:211], v[80:83]
	v_mfma_f32_16x16x32_bf16 v[68:71], v[172:175], v[216:219], v[68:71]
	v_mfma_f32_16x16x32_bf16 v[64:67], v[180:183], v[216:219], v[64:67]
	v_mfma_f32_16x16x32_bf16 v[116:119], v[176:179], v[196:199], v[116:119]
	v_mfma_f32_16x16x32_bf16 v[112:115], v[188:191], v[196:199], v[112:115]
	v_mfma_f32_16x16x32_bf16 v[100:103], v[176:179], v[204:207], v[100:103]
	v_mfma_f32_16x16x32_bf16 v[96:99], v[188:191], v[204:207], v[96:99]
	v_mfma_f32_16x16x32_bf16 v[84:87], v[176:179], v[212:215], v[84:87]
	v_mfma_f32_16x16x32_bf16 v[80:83], v[188:191], v[212:215], v[80:83]
	v_mfma_f32_16x16x32_bf16 v[68:71], v[176:179], v[220:223], v[68:71]
	v_mfma_f32_16x16x32_bf16 v[64:67], v[188:191], v[220:223], v[64:67]
	s_setprio 0
	s_barrier
	s_add_i32 s34, s49, s2
	v_lshl_add_u64 v[184:185], v[184:185], 0, s[18:19]
	s_mov_b32 m0, s34
	ds_read_b128 v[192:195], v153 offset:49152
	ds_read_b128 v[196:199], v153 offset:50176
	ds_read_b128 v[200:203], v153 offset:51200
	ds_read_b128 v[204:207], v153 offset:52224
	ds_read_b128 v[208:211], v153 offset:53248
	ds_read_b128 v[212:215], v153 offset:54272
	ds_read_b128 v[216:219], v153 offset:55296
	ds_read_b128 v[220:223], v153 offset:56320
	global_load_lds_dwordx4 v[184:185], off
	s_add_i32 m0, s34, 0x2000
	s_add_u32 s30, s30, 0x160080
	v_lshl_add_u64 v[184:185], v[224:225], 0, s[18:19]
	s_addc_u32 s31, s31, 0
	s_add_i32 s34, s51, s2
	global_load_lds_dwordx4 v[184:185], off
	v_lshl_add_u64 v[184:185], s[30:31], 0, v[130:131]
	s_mov_b32 m0, s34
	s_nop 0
	global_load_lds_dwordx4 v[184:185], off
	v_lshl_add_u64 v[184:185], s[30:31], 0, v[134:135]
	s_add_i32 m0, s34, 0x2000
	s_nop 0
	global_load_lds_dwordx4 v[184:185], off
	s_waitcnt vmcnt(6)
	s_waitcnt lgkmcnt(0)
	s_barrier
	s_setprio 3
	s_waitcnt lgkmcnt(0)
	v_mfma_f32_16x16x32_bf16 v[60:63], v[156:159], v[192:195], v[60:63]
	v_mfma_f32_16x16x32_bf16 v[56:59], v[164:167], v[192:195], v[56:59]
	v_mfma_f32_16x16x32_bf16 v[44:47], v[156:159], v[200:203], v[44:47]
	v_mfma_f32_16x16x32_bf16 v[40:43], v[164:167], v[200:203], v[40:43]
	v_mfma_f32_16x16x32_bf16 v[28:31], v[156:159], v[208:211], v[28:31]
	v_mfma_f32_16x16x32_bf16 v[24:27], v[164:167], v[208:211], v[24:27]
	v_mfma_f32_16x16x32_bf16 v[12:15], v[156:159], v[216:219], v[12:15]
	v_mfma_f32_16x16x32_bf16 v[8:11], v[164:167], v[216:219], v[8:11]
	v_mfma_f32_16x16x32_bf16 v[60:63], v[160:163], v[196:199], v[60:63]
	v_mfma_f32_16x16x32_bf16 v[56:59], v[168:171], v[196:199], v[56:59]
	v_mfma_f32_16x16x32_bf16 v[44:47], v[160:163], v[204:207], v[44:47]
	v_mfma_f32_16x16x32_bf16 v[40:43], v[168:171], v[204:207], v[40:43]
	v_mfma_f32_16x16x32_bf16 v[28:31], v[160:163], v[212:215], v[28:31]
	v_mfma_f32_16x16x32_bf16 v[24:27], v[168:171], v[212:215], v[24:27]
	v_mfma_f32_16x16x32_bf16 v[12:15], v[160:163], v[220:223], v[12:15]
	v_mfma_f32_16x16x32_bf16 v[8:11], v[168:171], v[220:223], v[8:11]
	s_setprio 0
	s_setprio 3
	v_mfma_f32_16x16x32_bf16 v[52:55], v[172:175], v[192:195], v[52:55]
	v_mfma_f32_16x16x32_bf16 v[48:51], v[180:183], v[192:195], v[48:51]
	v_mfma_f32_16x16x32_bf16 v[36:39], v[172:175], v[200:203], v[36:39]
	v_mfma_f32_16x16x32_bf16 v[32:35], v[180:183], v[200:203], v[32:35]
	v_mfma_f32_16x16x32_bf16 v[20:23], v[172:175], v[208:211], v[20:23]
	v_mfma_f32_16x16x32_bf16 v[16:19], v[180:183], v[208:211], v[16:19]
	v_mfma_f32_16x16x32_bf16 v[4:7], v[172:175], v[216:219], v[4:7]
	v_mfma_f32_16x16x32_bf16 v[0:3], v[180:183], v[216:219], v[0:3]
	v_mfma_f32_16x16x32_bf16 v[52:55], v[176:179], v[196:199], v[52:55]
	v_mfma_f32_16x16x32_bf16 v[48:51], v[188:191], v[196:199], v[48:51]
	v_mfma_f32_16x16x32_bf16 v[36:39], v[176:179], v[204:207], v[36:39]
	v_mfma_f32_16x16x32_bf16 v[32:35], v[188:191], v[204:207], v[32:35]
	v_mfma_f32_16x16x32_bf16 v[20:23], v[176:179], v[212:215], v[20:23]
	v_mfma_f32_16x16x32_bf16 v[16:19], v[188:191], v[212:215], v[16:19]
	v_mfma_f32_16x16x32_bf16 v[4:7], v[176:179], v[220:223], v[4:7]
	v_mfma_f32_16x16x32_bf16 v[0:3], v[188:191], v[220:223], v[0:3]
	s_setprio 0
	s_barrier
	s_add_i32 s48, s48, 2
	s_add_u32 s28, s28, 0x100
	s_addc_u32 s29, s29, 0
	s_cmpk_gt_u32 s48, 0x55
	s_cbranch_scc0 .LBB0_842
	s_branch .Lpeel_exit_3

; #define PG8_BAR __builtin_amdgcn_s_barrier()
; template <class Epi, class Sched>
; __device__ __forceinline__ void gemm_phase(LAS unsigned char* lds, const Gemm g, const Sched& S, const Epi& E, int tid_in) {
;     ...
;         if (wr == 0) PG8_BAR;
.Lpeel_exit_3:
	s_and_b64 vcc, exec, s[22:23]
	s_cbranch_vccz .LBB0_845
	s_barrier

;     __device__ bool next(int i, Unit& u) const { if (!b.next(i >> 1, u)) return false; u.half = i & 1; u.koff = (i & 1) * kbytes; return true; }
; #define PG8_STAGE(bufoff, gbase, voff) do { _Pragma("unroll") for (int _i = 0; _i < 2; ++_i) \
;         __builtin_amdgcn_global_load_lds((const unsigned*)((const char*)(gbase) + (voff)[_i]), (LAS unsigned*)(lds + (bufoff) + ldsw + _i * 8192), 16, 0, 0); } while (0)
; #define PG8_LDA(dst, b, h) do { _Pragma("unroll") for (int m = 0; m < 4; ++m) _Pragma("unroll") for (int k = 0; k < 2; ++k) dst[m][k] = *(const LAS bf16x8*)(lds + PG8_SA(b, h) + aoff + m * 2048 + k * 1024); } while (0)
; #define PG8_LDB(dst, b, h) do { _Pragma("unroll") for (int n = 0; n < 2; ++n) _Pragma("unroll") for (int k = 0; k < 2; ++k) dst[n][k] = *(const LAS bf16x8*)(lds + PG8_SB(b, h) + boff + n * 2048 + k * 1024); } while (0)
; #define PG8_WAIT_V(n) asm volatile("s_waitcnt vmcnt(" #n ")" ::: "memory")
; #define PG8_WAIT_L(n) asm volatile("s_waitcnt lgkmcnt(" #n ")" ::: "memory")
; #define PG8_BAR __builtin_amdgcn_s_barrier()
; #define PG8_SCHED __builtin_amdgcn_sched_barrier(0)
; template <class Epi, class Sched>
; __device__ __forceinline__ void gemm_phase(LAS unsigned char* lds, const Gemm g, const Sched& S, const Epi& E, int tid_in) {
;     ...
;         const bool has_next = S.next(ui + 1, nxt);
;         const char* nA = has_next ? (const char*)g.A + (size_t)nxt.pm * tstep + nxt.koff : cA; const char* nB = has_next ? (const char*)g.Bt + (size_t)nxt.pn * tstep + nxt.koff : cB;
;         for (int t = 0; t < nt; t += 2) {
;             const bool last = (t == nt - 2);
;             const char* a1 = cA + (size_t)(t + 1) * kstep;
;             const char* a2 = last ? nA : cA + (size_t)(t + 2) * kstep; const char* b2 = last ? nB : cB + (size_t)(t + 2) * kstep;
;             const char* a3 = a2 + kstep; const char* b3 = b2 + kstep;
;             PG8_LDB(B0, 0, 0); PG8_LDB(B1, 0, 1); PG8_SCHED; PG8_LDA(At, 0, 0); PG8_STAGE(PG8_SA(1, 0), a1, voffA); PG8_STAGE(PG8_SA(1, 1), a1 + hstep, voffA);
;             PG8_WAIT_V(8); PG8_WAIT_L(0); PG8_BAR; PG8_MMA(0, 0, At, B0); PG8_MMA(0, 1, At, B1); PG8_BAR; PG8_SCHED;
;             PG8_LDA(At, 0, 1); PG8_STAGE(PG8_SB(0, 0), b2, voffB); PG8_STAGE(PG8_SB(0, 1), b2 + hstep, voffB);
;             PG8_WAIT_V(6); PG8_WAIT_L(0); PG8_BAR; PG8_MMA(1, 0, At, B0); PG8_MMA(1, 1, At, B1); PG8_BAR; PG8_SCHED;
.LBB0_1008:
	s_ashr_i32 s23, s22, 31
	s_lshl_b64 s[24:25], s[22:23], 20
	s_add_u32 s24, s58, s24
	s_addc_u32 s25, s59, s25
	s_and_b64 s[26:27], s[4:5], exec
	s_cselect_b32 s23, s25, s31
	s_cselect_b32 s29, s24, s30
	s_ashr_i32 s21, s20, 31
	s_lshl_b64 s[26:27], s[20:21], 20
	s_add_u32 s26, s60, s26
	s_addc_u32 s27, s61, s27
	s_and_b64 s[36:37], s[4:5], exec
	s_cselect_b32 s21, s27, s35
	s_cselect_b32 s47, s26, s34
	s_add_u32 s48, s34, 0x100
	v_lshl_add_u64 v[144:145], s[30:31], 0, v[136:137]
	v_lshl_add_u64 v[146:147], s[30:31], 0, v[138:139]
	s_addc_u32 s49, s35, 0
	s_mov_b32 s51, -2
	s_mov_b64 s[34:35], 0
	s_waitcnt lgkmcnt(0)
	ds_read_b128 v[158:161], v153
	ds_read_b128 v[162:165], v153 offset:1024
	ds_read_b128 v[166:169], v153 offset:2048
	ds_read_b128 v[170:173], v153 offset:3072
	ds_read_b128 v[174:177], v154
	ds_read_b128 v[178:181], v154 offset:1024
	ds_read_b128 v[182:185], v154 offset:2048
	ds_read_b128 v[188:191], v154 offset:3072
	s_add_u32 s36, s30, s34
	s_addc_u32 s37, s31, s35
	s_add_u32 s38, s36, 0x100
	s_addc_u32 s39, s37, 0
	s_add_u32 s36, s48, s34
	s_addc_u32 s37, s49, s35
	s_cmpk_eq_i32 s34, 0xf00
	s_cselect_b32 s37, s21, s37
	s_cselect_b32 s36, s47, s36
	s_cselect_b32 s39, s23, s39
	s_cselect_b32 s38, s29, s38
	v_lshl_add_u64 v[148:149], v[146:147], 0, s[34:35]
	v_lshl_add_u64 v[186:187], v[148:149], 0, s[14:15]
	s_add_i32 m0, s3, 0x8000
	ds_read_b128 v[192:195], v155
	ds_read_b128 v[196:199], v155 offset:1024
	ds_read_b128 v[200:203], v155 offset:2048
	ds_read_b128 v[204:207], v155 offset:3072
	ds_read_b128 v[208:211], v155 offset:4096
	ds_read_b128 v[212:215], v155 offset:5120
	ds_read_b128 v[216:219], v155 offset:6144
	ds_read_b128 v[220:223], v155 offset:7168
	global_load_lds_dwordx4 v[186:187], off
	v_lshl_add_u64 v[186:187], v[144:145], 0, s[34:35]
	v_lshl_add_u64 v[224:225], v[186:187], 0, s[14:15]
	s_add_i32 m0, s3, 0xa000
	v_lshl_add_u64 v[148:149], v[148:149], 0, s[16:17]
	global_load_lds_dwordx4 v[224:225], off
	s_add_i32 m0, s3, 0xc000
	s_nop 0
	global_load_lds_dwordx4 v[148:149], off
	v_lshl_add_u64 v[148:149], v[186:187], 0, s[16:17]
	s_add_i32 m0, s3, 0xe000
	s_nop 0
	global_load_lds_dwordx4 v[148:149], off
	s_waitcnt vmcnt(8)
	s_waitcnt lgkmcnt(0)
	s_barrier
	s_setprio 3
	s_waitcnt lgkmcnt(0)
	v_mfma_f32_16x16x32_bf16 v[124:127], v[158:161], v[192:195], 0
	v_mfma_f32_16x16x32_bf16 v[120:123], v[166:169], v[192:195], 0
	v_mfma_f32_16x16x32_bf16 v[108:111], v[158:161], v[200:203], 0
	v_mfma_f32_16x16x32_bf16 v[104:107], v[166:169], v[200:203], 0
	v_mfma_f32_16x16x32_bf16 v[92:95], v[158:161], v[208:211], 0
	v_mfma_f32_16x16x32_bf16 v[88:91], v[166:169], v[208:211], 0
	v_mfma_f32_16x16x32_bf16 v[76:79], v[158:161], v[216:219], 0
	v_mfma_f32_16x16x32_bf16 v[72:75], v[166:169], v[216:219], 0
	v_mfma_f32_16x16x32_bf16 v[124:127], v[162:165], v[196:199], v[124:127]
	v_mfma_f32_16x16x32_bf16 v[120:123], v[170:173], v[196:199], v[120:123]
	v_mfma_f32_16x16x32_bf16 v[108:111], v[162:165], v[204:207], v[108:111]
	v_mfma_f32_16x16x32_bf16 v[104:107], v[170:173], v[204:207], v[104:107]
	v_mfma_f32_16x16x32_bf16 v[92:95], v[162:165], v[212:215], v[92:95]
	v_mfma_f32_16x16x32_bf16 v[88:91], v[170:173], v[212:215], v[88:91]
	v_mfma_f32_16x16x32_bf16 v[76:79], v[162:165], v[220:223], v[76:79]
	v_mfma_f32_16x16x32_bf16 v[72:75], v[170:173], v[220:223], v[72:75]
	s_setprio 0
	s_setprio 3
	v_mfma_f32_16x16x32_bf16 v[116:119], v[174:177], v[192:195], 0
	v_mfma_f32_16x16x32_bf16 v[112:115], v[182:185], v[192:195], 0
	v_mfma_f32_16x16x32_bf16 v[100:103], v[174:177], v[200:203], 0
	v_mfma_f32_16x16x32_bf16 v[96:99], v[182:185], v[200:203], 0
	v_mfma_f32_16x16x32_bf16 v[84:87], v[174:177], v[208:211], 0
	v_mfma_f32_16x16x32_bf16 v[80:83], v[182:185], v[208:211], 0
	v_mfma_f32_16x16x32_bf16 v[68:71], v[174:177], v[216:219], 0
	v_mfma_f32_16x16x32_bf16 v[64:67], v[182:185], v[216:219], 0
	v_mfma_f32_16x16x32_bf16 v[116:119], v[178:181], v[196:199], v[116:119]
	v_mfma_f32_16x16x32_bf16 v[112:115], v[188:191], v[196:199], v[112:115]
	v_mfma_f32_16x16x32_bf16 v[100:103], v[178:181], v[204:207], v[100:103]
	v_mfma_f32_16x16x32_bf16 v[96:99], v[188:191], v[204:207], v[96:99]
	v_mfma_f32_16x16x32_bf16 v[84:87], v[178:181], v[212:215], v[84:87]
	v_mfma_f32_16x16x32_bf16 v[80:83], v[188:191], v[212:215], v[80:83]
	v_mfma_f32_16x16x32_bf16 v[68:71], v[178:181], v[220:223], v[68:71]
	v_mfma_f32_16x16x32_bf16 v[64:67], v[188:191], v[220:223], v[64:67]
	s_setprio 0
	s_barrier
	s_add_i32 s62, s44, s2
	v_lshl_add_u64 v[148:149], s[36:37], 0, v[130:131]
	s_mov_b32 m0, s62
	ds_read_b128 v[192:195], v155 offset:16384
	ds_read_b128 v[196:199], v155 offset:17408
	ds_read_b128 v[200:203], v155 offset:18432
	ds_read_b128 v[204:207], v155 offset:19456
	ds_read_b128 v[208:211], v155 offset:20480
	ds_read_b128 v[212:215], v155 offset:21504
	ds_read_b128 v[216:219], v155 offset:22528
	ds_read_b128 v[220:223], v155 offset:23552
	global_load_lds_dwordx4 v[148:149], off
	s_add_i32 m0, s62, 0x2000
	s_add_u32 s62, s36, 0x80000
	v_lshl_add_u64 v[186:187], s[36:37], 0, v[134:135]
	s_addc_u32 s63, s37, 0
	s_add_i32 s64, s45, s2
	global_load_lds_dwordx4 v[186:187], off
	v_lshl_add_u64 v[224:225], s[62:63], 0, v[130:131]
	s_mov_b32 m0, s64
	s_nop 0
	global_load_lds_dwordx4 v[224:225], off
	v_lshl_add_u64 v[224:225], s[62:63], 0, v[134:135]
	s_add_i32 m0, s64, 0x2000
	s_nop 0
	global_load_lds_dwordx4 v[224:225], off
	s_waitcnt vmcnt(6)
	s_waitcnt lgkmcnt(0)
	s_barrier
; #define PG8_STAGE(bufoff, gbase, voff) do { _Pragma("unroll") for (int _i = 0; _i < 2; ++_i) \
;         __builtin_amdgcn_global_load_lds((const unsigned*)((const char*)(gbase) + (voff)[_i]), (LAS unsigned*)(lds + (bufoff) + ldsw + _i * 8192), 16, 0, 0); } while (0)
; #define PG8_LDA(dst, b, h) do { _Pragma("unroll") for (int m = 0; m < 4; ++m) _Pragma("unroll") for (int k = 0; k < 2; ++k) dst[m][k] = *(const LAS bf16x8*)(lds + PG8_SA(b, h) + aoff + m * 2048 + k * 1024); } while (0)
; #define PG8_LDB(dst, b, h) do { _Pragma("unroll") for (int n = 0; n < 2; ++n) _Pragma("unroll") for (int k = 0; k < 2; ++k) dst[n][k] = *(const LAS bf16x8*)(lds + PG8_SB(b, h) + boff + n * 2048 + k * 1024); } while (0)
; #define PG8_MMA(ai, bj, At, Bt) do { __builtin_amdgcn_s_setprio(3); _Pragma("unroll") for (int m = 0; m < 4; ++m) _Pragma("unroll") for (int n = 0; n < 2; ++n) _Pragma("unroll") for (int k = 0; k < 2; ++k) \
;         acc[ai][bj][m][n] = __builtin_amdgcn_mfma_f32_16x16x32_bf16(Bt[n][k], At[m][k], acc[ai][bj][m][n], 0, 0, 0); __builtin_amdgcn_s_setprio(0); } while (0)
; #define PG8_WAIT_V(n) asm volatile("s_waitcnt vmcnt(" #n ")" ::: "memory")
; #define PG8_WAIT_L(n) asm volatile("s_waitcnt lgkmcnt(" #n ")" ::: "memory")
; #define PG8_BAR __builtin_amdgcn_s_barrier()
; #define PG8_SCHED __builtin_amdgcn_sched_barrier(0)
; template <class Epi, class Sched>
; __device__ __forceinline__ void gemm_phase(LAS unsigned char* lds, const Gemm g, const Sched& S, const Epi& E, int tid_in) {
;     ...
;             PG8_WAIT_V(6); PG8_WAIT_L(0); PG8_BAR; PG8_MMA(1, 0, At, B0); PG8_MMA(1, 1, At, B1); PG8_BAR; PG8_SCHED;
;             PG8_LDB(B0, 1, 0); PG8_LDB(B1, 1, 1); PG8_SCHED; PG8_LDA(At, 1, 0); PG8_STAGE(PG8_SA(0, 0), a2, voffA); PG8_STAGE(PG8_SA(0, 1), a2 + hstep, voffA);
;             PG8_WAIT_V(8); PG8_WAIT_L(0); PG8_BAR; PG8_MMA(0, 0, At, B0); PG8_MMA(0, 1, At, B1); PG8_BAR; PG8_SCHED;
	s_setprio 3
	s_waitcnt lgkmcnt(0)
	v_mfma_f32_16x16x32_bf16 v[60:63], v[158:161], v[192:195], 0
	v_mfma_f32_16x16x32_bf16 v[56:59], v[166:169], v[192:195], 0
	v_mfma_f32_16x16x32_bf16 v[44:47], v[158:161], v[200:203], 0
	v_mfma_f32_16x16x32_bf16 v[40:43], v[166:169], v[200:203], 0
	v_mfma_f32_16x16x32_bf16 v[28:31], v[158:161], v[208:211], 0
	v_mfma_f32_16x16x32_bf16 v[24:27], v[166:169], v[208:211], 0
	v_mfma_f32_16x16x32_bf16 v[12:15], v[158:161], v[216:219], 0
	v_mfma_f32_16x16x32_bf16 v[8:11], v[166:169], v[216:219], 0
	v_mfma_f32_16x16x32_bf16 v[60:63], v[162:165], v[196:199], v[60:63]
	v_mfma_f32_16x16x32_bf16 v[56:59], v[170:173], v[196:199], v[56:59]
	v_mfma_f32_16x16x32_bf16 v[44:47], v[162:165], v[204:207], v[44:47]
	v_mfma_f32_16x16x32_bf16 v[40:43], v[170:173], v[204:207], v[40:43]
	v_mfma_f32_16x16x32_bf16 v[28:31], v[162:165], v[212:215], v[28:31]
	v_mfma_f32_16x16x32_bf16 v[24:27], v[170:173], v[212:215], v[24:27]
	v_mfma_f32_16x16x32_bf16 v[12:15], v[162:165], v[220:223], v[12:15]
	v_mfma_f32_16x16x32_bf16 v[8:11], v[170:173], v[220:223], v[8:11]
	s_setprio 0
	s_setprio 3
	v_mfma_f32_16x16x32_bf16 v[52:55], v[174:177], v[192:195], 0
	v_mfma_f32_16x16x32_bf16 v[48:51], v[182:185], v[192:195], 0
	v_mfma_f32_16x16x32_bf16 v[36:39], v[174:177], v[200:203], 0
	v_mfma_f32_16x16x32_bf16 v[32:35], v[182:185], v[200:203], 0
	v_mfma_f32_16x16x32_bf16 v[20:23], v[174:177], v[208:211], 0
	v_mfma_f32_16x16x32_bf16 v[16:19], v[182:185], v[208:211], 0
	v_mfma_f32_16x16x32_bf16 v[4:7], v[174:177], v[216:219], 0
	v_mfma_f32_16x16x32_bf16 v[0:3], v[182:185], v[216:219], 0
	v_mfma_f32_16x16x32_bf16 v[52:55], v[178:181], v[196:199], v[52:55]
	v_mfma_f32_16x16x32_bf16 v[48:51], v[188:191], v[196:199], v[48:51]
	v_mfma_f32_16x16x32_bf16 v[36:39], v[178:181], v[204:207], v[36:39]
	v_mfma_f32_16x16x32_bf16 v[32:35], v[188:191], v[204:207], v[32:35]
	v_mfma_f32_16x16x32_bf16 v[20:23], v[178:181], v[212:215], v[20:23]
	v_mfma_f32_16x16x32_bf16 v[16:19], v[188:191], v[212:215], v[16:19]
	v_mfma_f32_16x16x32_bf16 v[4:7], v[178:181], v[220:223], v[4:7]
	v_mfma_f32_16x16x32_bf16 v[0:3], v[188:191], v[220:223], v[0:3]
	s_setprio 0
	s_barrier
	s_add_i32 s62, 0, 0x18000
	v_add_u32_e32 v157, s62, v151
	s_add_i32 s63, 0, 0x1c000
	ds_read_b128 v[158:161], v157
	ds_read_b128 v[162:165], v157 offset:1024
	ds_read_b128 v[166:169], v157 offset:2048
	ds_read_b128 v[170:173], v157 offset:3072
	v_add_u32_e32 v157, s63, v151
	ds_read_b128 v[174:177], v157
	ds_read_b128 v[178:181], v157 offset:1024
	ds_read_b128 v[182:185], v157 offset:2048
	ds_read_b128 v[188:191], v157 offset:3072
	s_mov_b32 m0, s3
	v_lshl_add_u64 v[224:225], s[38:39], 0, v[128:129]
	ds_read_b128 v[192:195], v155 offset:32768
	ds_read_b128 v[196:199], v155 offset:33792
	ds_read_b128 v[200:203], v155 offset:34816
	ds_read_b128 v[204:207], v155 offset:35840
	ds_read_b128 v[208:211], v155 offset:36864
	ds_read_b128 v[212:215], v155 offset:37888
	ds_read_b128 v[216:219], v155 offset:38912
	ds_read_b128 v[220:223], v155 offset:39936
	global_load_lds_dwordx4 v[224:225], off
	v_lshl_add_u64 v[224:225], s[38:39], 0, v[132:133]
	s_add_u32 s38, s38, 0x80000
	s_mov_b32 m0, s40
	s_addc_u32 s39, s39, 0
	global_load_lds_dwordx4 v[224:225], off
	v_lshl_add_u64 v[224:225], s[38:39], 0, v[128:129]
	s_mov_b32 m0, s41
	s_nop 0
	global_load_lds_dwordx4 v[224:225], off
	v_lshl_add_u64 v[224:225], s[38:39], 0, v[132:133]
	s_mov_b32 m0, s42
	s_nop 0
	global_load_lds_dwordx4 v[224:225], off
	s_waitcnt vmcnt(8)
	s_waitcnt lgkmcnt(0)
	s_barrier
; #define PG8_STAGE(bufoff, gbase, voff) do { _Pragma("unroll") for (int _i = 0; _i < 2; ++_i) \
;         __builtin_amdgcn_global_load_lds((const unsigned*)((const char*)(gbase) + (voff)[_i]), (LAS unsigned*)(lds + (bufoff) + ldsw + _i * 8192), 16, 0, 0); } while (0)
; #define PG8_LDA(dst, b, h) do { _Pragma("unroll") for (int m = 0; m < 4; ++m) _Pragma("unroll") for (int k = 0; k < 2; ++k) dst[m][k] = *(const LAS bf16x8*)(lds + PG8_SA(b, h) + aoff + m * 2048 + k * 1024); } while (0)
; #define PG8_MMA(ai, bj, At, Bt) do { __builtin_amdgcn_s_setprio(3); _Pragma("unroll") for (int m = 0; m < 4; ++m) _Pragma("unroll") for (int n = 0; n < 2; ++n) _Pragma("unroll") for (int k = 0; k < 2; ++k) \
;         acc[ai][bj][m][n] = __builtin_amdgcn_mfma_f32_16x16x32_bf16(Bt[n][k], At[m][k], acc[ai][bj][m][n], 0, 0, 0); __builtin_amdgcn_s_setprio(0); } while (0)
; #define PG8_WAIT_V(n) asm volatile("s_waitcnt vmcnt(" #n ")" ::: "memory")
; #define PG8_WAIT_L(n) asm volatile("s_waitcnt lgkmcnt(" #n ")" ::: "memory")
; #define PG8_BAR __builtin_amdgcn_s_barrier()
; #define PG8_SCHED __builtin_amdgcn_sched_barrier(0)
; template <class Epi, class Sched>
; __device__ __forceinline__ void gemm_phase(LAS unsigned char* lds, const Gemm g, const Sched& S, const Epi& E, int tid_in) {
;     ...
;             PG8_WAIT_V(8); PG8_WAIT_L(0); PG8_BAR; PG8_MMA(0, 0, At, B0); PG8_MMA(0, 1, At, B1); PG8_BAR; PG8_SCHED;
;             PG8_LDA(At, 1, 1); PG8_STAGE(PG8_SB(1, 0), b3, voffB); PG8_STAGE(PG8_SB(1, 1), b3 + hstep, voffB);
;             PG8_WAIT_V(6); PG8_WAIT_L(0); PG8_BAR; PG8_MMA(1, 0, At, B0); PG8_MMA(1, 1, At, B1); PG8_BAR; PG8_SCHED;
;         }
	s_setprio 3
	s_waitcnt lgkmcnt(0)
	v_mfma_f32_16x16x32_bf16 v[124:127], v[158:161], v[192:195], v[124:127]
	v_mfma_f32_16x16x32_bf16 v[120:123], v[166:169], v[192:195], v[120:123]
	v_mfma_f32_16x16x32_bf16 v[108:111], v[158:161], v[200:203], v[108:111]
	v_mfma_f32_16x16x32_bf16 v[104:107], v[166:169], v[200:203], v[104:107]
	v_mfma_f32_16x16x32_bf16 v[92:95], v[158:161], v[208:211], v[92:95]
	v_mfma_f32_16x16x32_bf16 v[88:91], v[166:169], v[208:211], v[88:91]
	v_mfma_f32_16x16x32_bf16 v[76:79], v[158:161], v[216:219], v[76:79]
	v_mfma_f32_16x16x32_bf16 v[72:75], v[166:169], v[216:219], v[72:75]
	v_mfma_f32_16x16x32_bf16 v[124:127], v[162:165], v[196:199], v[124:127]
	v_mfma_f32_16x16x32_bf16 v[120:123], v[170:173], v[196:199], v[120:123]
	v_mfma_f32_16x16x32_bf16 v[108:111], v[162:165], v[204:207], v[108:111]
	v_mfma_f32_16x16x32_bf16 v[104:107], v[170:173], v[204:207], v[104:107]
	v_mfma_f32_16x16x32_bf16 v[92:95], v[162:165], v[212:215], v[92:95]
	v_mfma_f32_16x16x32_bf16 v[88:91], v[170:173], v[212:215], v[88:91]
	v_mfma_f32_16x16x32_bf16 v[76:79], v[162:165], v[220:223], v[76:79]
	v_mfma_f32_16x16x32_bf16 v[72:75], v[170:173], v[220:223], v[72:75]
	s_setprio 0
	s_setprio 3
	v_mfma_f32_16x16x32_bf16 v[116:119], v[174:177], v[192:195], v[116:119]
	v_mfma_f32_16x16x32_bf16 v[112:115], v[182:185], v[192:195], v[112:115]
	v_mfma_f32_16x16x32_bf16 v[100:103], v[174:177], v[200:203], v[100:103]
	v_mfma_f32_16x16x32_bf16 v[96:99], v[182:185], v[200:203], v[96:99]
	v_mfma_f32_16x16x32_bf16 v[84:87], v[174:177], v[208:211], v[84:87]
	v_mfma_f32_16x16x32_bf16 v[80:83], v[182:185], v[208:211], v[80:83]
	v_mfma_f32_16x16x32_bf16 v[68:71], v[174:177], v[216:219], v[68:71]
	v_mfma_f32_16x16x32_bf16 v[64:67], v[182:185], v[216:219], v[64:67]
	v_mfma_f32_16x16x32_bf16 v[116:119], v[178:181], v[196:199], v[116:119]
	v_mfma_f32_16x16x32_bf16 v[112:115], v[188:191], v[196:199], v[112:115]
	v_mfma_f32_16x16x32_bf16 v[100:103], v[178:181], v[204:207], v[100:103]
	v_mfma_f32_16x16x32_bf16 v[96:99], v[188:191], v[204:207], v[96:99]
	v_mfma_f32_16x16x32_bf16 v[84:87], v[178:181], v[212:215], v[84:87]
	v_mfma_f32_16x16x32_bf16 v[80:83], v[188:191], v[212:215], v[80:83]
	v_mfma_f32_16x16x32_bf16 v[68:71], v[178:181], v[220:223], v[68:71]
	v_mfma_f32_16x16x32_bf16 v[64:67], v[188:191], v[220:223], v[64:67]
	s_setprio 0
	s_barrier
	s_add_i32 s38, s62, s2
	v_lshl_add_u64 v[148:149], v[148:149], 0, s[14:15]
	s_mov_b32 m0, s38
	ds_read_b128 v[192:195], v155 offset:49152
	ds_read_b128 v[196:199], v155 offset:50176
	ds_read_b128 v[200:203], v155 offset:51200
	ds_read_b128 v[204:207], v155 offset:52224
	ds_read_b128 v[208:211], v155 offset:53248
	ds_read_b128 v[212:215], v155 offset:54272
	ds_read_b128 v[216:219], v155 offset:55296
	ds_read_b128 v[220:223], v155 offset:56320
	global_load_lds_dwordx4 v[148:149], off
	s_add_i32 m0, s38, 0x2000
	s_add_u32 s36, s36, 0x80080
	v_lshl_add_u64 v[148:149], v[186:187], 0, s[14:15]
	s_addc_u32 s37, s37, 0
	s_add_i32 s38, s63, s2
	global_load_lds_dwordx4 v[148:149], off
	v_lshl_add_u64 v[148:149], s[36:37], 0, v[130:131]
	s_mov_b32 m0, s38
	s_nop 0
	global_load_lds_dwordx4 v[148:149], off
	v_lshl_add_u64 v[148:149], s[36:37], 0, v[134:135]
	s_add_i32 m0, s38, 0x2000
	s_nop 0
	global_load_lds_dwordx4 v[148:149], off
	s_waitcnt vmcnt(6)
	s_waitcnt lgkmcnt(0)
	s_barrier
	s_setprio 3
	s_waitcnt lgkmcnt(0)
	v_mfma_f32_16x16x32_bf16 v[60:63], v[158:161], v[192:195], v[60:63]
	v_mfma_f32_16x16x32_bf16 v[56:59], v[166:169], v[192:195], v[56:59]
	v_mfma_f32_16x16x32_bf16 v[44:47], v[158:161], v[200:203], v[44:47]
	v_mfma_f32_16x16x32_bf16 v[40:43], v[166:169], v[200:203], v[40:43]
	v_mfma_f32_16x16x32_bf16 v[28:31], v[158:161], v[208:211], v[28:31]
	v_mfma_f32_16x16x32_bf16 v[24:27], v[166:169], v[208:211], v[24:27]
	v_mfma_f32_16x16x32_bf16 v[12:15], v[158:161], v[216:219], v[12:15]
	v_mfma_f32_16x16x32_bf16 v[8:11], v[166:169], v[216:219], v[8:11]
	v_mfma_f32_16x16x32_bf16 v[60:63], v[162:165], v[196:199], v[60:63]
	v_mfma_f32_16x16x32_bf16 v[56:59], v[170:173], v[196:199], v[56:59]
	v_mfma_f32_16x16x32_bf16 v[44:47], v[162:165], v[204:207], v[44:47]
	v_mfma_f32_16x16x32_bf16 v[40:43], v[170:173], v[204:207], v[40:43]
	v_mfma_f32_16x16x32_bf16 v[28:31], v[162:165], v[212:215], v[28:31]
	v_mfma_f32_16x16x32_bf16 v[24:27], v[170:173], v[212:215], v[24:27]
	v_mfma_f32_16x16x32_bf16 v[12:15], v[162:165], v[220:223], v[12:15]
	v_mfma_f32_16x16x32_bf16 v[8:11], v[170:173], v[220:223], v[8:11]
	s_setprio 0
	s_setprio 3
	v_mfma_f32_16x16x32_bf16 v[52:55], v[174:177], v[192:195], v[52:55]
	v_mfma_f32_16x16x32_bf16 v[48:51], v[182:185], v[192:195], v[48:51]
	v_mfma_f32_16x16x32_bf16 v[36:39], v[174:177], v[200:203], v[36:39]
	v_mfma_f32_16x16x32_bf16 v[32:35], v[182:185], v[200:203], v[32:35]
	v_mfma_f32_16x16x32_bf16 v[20:23], v[174:177], v[208:211], v[20:23]
	v_mfma_f32_16x16x32_bf16 v[16:19], v[182:185], v[208:211], v[16:19]
	v_mfma_f32_16x16x32_bf16 v[4:7], v[174:177], v[216:219], v[4:7]
	v_mfma_f32_16x16x32_bf16 v[0:3], v[182:185], v[216:219], v[0:3]
	v_mfma_f32_16x16x32_bf16 v[52:55], v[178:181], v[196:199], v[52:55]
	v_mfma_f32_16x16x32_bf16 v[48:51], v[188:191], v[196:199], v[48:51]
	v_mfma_f32_16x16x32_bf16 v[36:39], v[178:181], v[204:207], v[36:39]
	v_mfma_f32_16x16x32_bf16 v[32:35], v[188:191], v[204:207], v[32:35]
	v_mfma_f32_16x16x32_bf16 v[20:23], v[178:181], v[212:215], v[20:23]
	v_mfma_f32_16x16x32_bf16 v[16:19], v[188:191], v[212:215], v[16:19]
	v_mfma_f32_16x16x32_bf16 v[4:7], v[178:181], v[220:223], v[4:7]
	v_mfma_f32_16x16x32_bf16 v[0:3], v[188:191], v[220:223], v[0:3]
	s_setprio 0
	s_barrier
	s_add_i32 s51, s51, 2
	s_add_u32 s34, s34, 0x100
	s_addc_u32 s35, s35, 0
	s_cmp_gt_u32 s51, 29
	s_cbranch_scc0 .LBB0_1009
	s_branch .Lpeel_exit_4

; #define PG8_BAR __builtin_amdgcn_s_barrier()
; template <class Epi, class Sched>
; __device__ __forceinline__ void gemm_phase(LAS unsigned char* lds, const Gemm g, const Sched& S, const Epi& E, int tid_in) {
;     ...
;         if (wr == 0) PG8_BAR;
.Lpeel_exit_4:
	s_and_b64 vcc, exec, s[18:19]
	s_cbranch_vccz .LBB0_1012
	s_barrier
